# GEMM K-loops: per-block priority flips removed, waves 4-7 run each tile's K-loop at static priority 1
# baseline (speedup 1.0000x reference)
.LBB0_92:
	s_ashr_i32 s13, s12, 31
	s_lshl_b64 s[14:15], s[12:13], 20
	v_readlane_b32 s16, v254, 57
	v_readlane_b32 s17, v254, 58
	s_add_u32 s14, s16, s14
	s_addc_u32 s15, s17, s15
	s_and_b64 s[16:17], s[38:39], exec
	s_cselect_b32 s13, s15, s19
	s_cselect_b32 s40, s14, s18
	s_ashr_i32 s11, s10, 31
	s_lshl_b64 s[16:17], s[10:11], 20
	s_add_u32 s16, s24, s16
	s_addc_u32 s17, s25, s17
	s_and_b64 s[22:23], s[38:39], exec
	s_cselect_b32 s11, s17, s21
	s_cselect_b32 s41, s16, s20
	s_add_u32 s18, s18, 0x80080
	s_addc_u32 s19, s19, 0
	s_add_u32 s42, s20, 0x100
	v_mov_b32_e32 v0, 0
	s_addc_u32 s43, s21, 0
	s_mov_b32 s44, -2
	v_mov_b32_e32 v1, v0
	v_mov_b32_e32 v2, v0
	v_mov_b32_e32 v3, v0
	v_mov_b32_e32 v8, v0
	v_mov_b32_e32 v9, v0
	v_mov_b32_e32 v10, v0
	v_mov_b32_e32 v11, v0
	v_mov_b32_e32 v16, v0
	v_mov_b32_e32 v17, v0
	v_mov_b32_e32 v18, v0
	v_mov_b32_e32 v19, v0
	v_mov_b32_e32 v24, v0
	v_mov_b32_e32 v25, v0
	v_mov_b32_e32 v26, v0
	v_mov_b32_e32 v27, v0
	v_mov_b32_e32 v32, v0
	v_mov_b32_e32 v33, v0
	v_mov_b32_e32 v34, v0
	v_mov_b32_e32 v35, v0
	v_mov_b32_e32 v40, v0
	v_mov_b32_e32 v41, v0
	v_mov_b32_e32 v42, v0
	v_mov_b32_e32 v43, v0
	v_mov_b32_e32 v48, v0
	v_mov_b32_e32 v49, v0
	v_mov_b32_e32 v50, v0
	v_mov_b32_e32 v51, v0
	v_mov_b32_e32 v56, v0
	v_mov_b32_e32 v57, v0
	v_mov_b32_e32 v58, v0
	v_mov_b32_e32 v59, v0
	v_mov_b32_e32 v4, v0
	v_mov_b32_e32 v5, v0
	v_mov_b32_e32 v6, v0
	v_mov_b32_e32 v7, v0
	v_mov_b32_e32 v12, v0
	v_mov_b32_e32 v13, v0
	v_mov_b32_e32 v14, v0
	v_mov_b32_e32 v15, v0
	v_mov_b32_e32 v20, v0
	v_mov_b32_e32 v21, v0
	v_mov_b32_e32 v22, v0
	v_mov_b32_e32 v23, v0
	v_mov_b32_e32 v28, v0
	v_mov_b32_e32 v29, v0
	v_mov_b32_e32 v30, v0
	v_mov_b32_e32 v31, v0
	v_mov_b32_e32 v36, v0
	v_mov_b32_e32 v37, v0
	v_mov_b32_e32 v38, v0
	v_mov_b32_e32 v39, v0
	v_mov_b32_e32 v44, v0
	v_mov_b32_e32 v45, v0
	v_mov_b32_e32 v46, v0
	v_mov_b32_e32 v47, v0
	v_mov_b32_e32 v52, v0
	v_mov_b32_e32 v53, v0
	v_mov_b32_e32 v54, v0
	v_mov_b32_e32 v55, v0
	v_mov_b32_e32 v60, v0
	v_mov_b32_e32 v61, v0
	v_mov_b32_e32 v62, v0
	v_mov_b32_e32 v63, v0
	v_mov_b32_e32 v66, v0
	v_mov_b32_e32 v67, v0
	v_mov_b32_e32 v68, v0
	v_mov_b32_e32 v69, v0
	v_mov_b32_e32 v74, v0
	v_mov_b32_e32 v75, v0
	v_mov_b32_e32 v76, v0
	v_mov_b32_e32 v77, v0
	v_mov_b32_e32 v82, v0
	v_mov_b32_e32 v83, v0
	v_mov_b32_e32 v84, v0
	v_mov_b32_e32 v85, v0
	v_mov_b32_e32 v90, v0
	v_mov_b32_e32 v91, v0
	v_mov_b32_e32 v92, v0
	v_mov_b32_e32 v93, v0
	v_mov_b32_e32 v98, v0
	v_mov_b32_e32 v99, v0
	v_mov_b32_e32 v100, v0
	v_mov_b32_e32 v101, v0
	v_mov_b32_e32 v106, v0
	v_mov_b32_e32 v107, v0
	v_mov_b32_e32 v108, v0
	v_mov_b32_e32 v109, v0
	v_mov_b32_e32 v114, v0
	v_mov_b32_e32 v115, v0
	v_mov_b32_e32 v116, v0
	v_mov_b32_e32 v117, v0
	v_mov_b32_e32 v122, v0
	v_mov_b32_e32 v123, v0
	v_mov_b32_e32 v124, v0
	v_mov_b32_e32 v125, v0
	v_mov_b32_e32 v70, v0
	v_mov_b32_e32 v71, v0
	v_mov_b32_e32 v72, v0
	v_mov_b32_e32 v73, v0
	v_mov_b32_e32 v78, v0
	v_mov_b32_e32 v79, v0
	v_mov_b32_e32 v80, v0
	v_mov_b32_e32 v81, v0
	v_mov_b32_e32 v86, v0
	v_mov_b32_e32 v87, v0
	v_mov_b32_e32 v88, v0
	v_mov_b32_e32 v89, v0
	v_mov_b32_e32 v94, v0
	v_mov_b32_e32 v95, v0
	v_mov_b32_e32 v96, v0
	v_mov_b32_e32 v97, v0
	v_mov_b32_e32 v102, v0
	v_mov_b32_e32 v103, v0
	v_mov_b32_e32 v104, v0
	v_mov_b32_e32 v105, v0
	v_mov_b32_e32 v110, v0
	v_mov_b32_e32 v111, v0
	v_mov_b32_e32 v112, v0
	v_mov_b32_e32 v113, v0
	v_mov_b32_e32 v118, v0
	v_mov_b32_e32 v119, v0
	v_mov_b32_e32 v120, v0
	v_mov_b32_e32 v121, v0
	v_mov_b32_e32 v126, v0
	v_mov_b32_e32 v127, v0
	v_mov_b32_e32 v128, v0
	v_mov_b32_e32 v129, v0
	v_readfirstlane_b32 s98, v186
	s_cmpk_lt_u32 s98, 0x100
	s_cbranch_scc1 .Lgp_skip1
	s_setprio 1
.Lgp_skip1:
.LBB0_93:
	s_add_u32 s20, s18, 0xfff80080
	s_addc_u32 s21, s19, -1
	s_add_i32 s45, 0, 0x10000
	s_cmp_eq_u32 s44, 28
	s_cselect_b32 s23, s13, s21
	s_cselect_b32 s22, s40, s20
	v_add_u32_e32 v142, s45, v145
	s_cselect_b32 s21, s11, s43
	s_cselect_b32 s20, s41, s42
	s_add_i32 s48, 0, 0x14000
	ds_read_b128 v[148:151], v142
	ds_read_b128 v[152:155], v142 offset:1024
	ds_read_b128 v[156:159], v142 offset:2048
	ds_read_b128 v[174:177], v142 offset:3072
	v_add_u32_e32 v142, s48, v145
	ds_read_b128 v[178:181], v142
	ds_read_b128 v[182:185], v142 offset:1024
	ds_read_b128 v[200:203], v142 offset:2048
	ds_read_b128 v[204:207], v142 offset:3072
	v_lshl_add_u64 v[142:143], s[18:19], 0, v[138:139]
	s_add_i32 m0, s27, 0xc000
	ds_read_b128 v[208:211], v146
	ds_read_b128 v[212:215], v146 offset:1024
	ds_read_b128 v[216:219], v146 offset:2048
	ds_read_b128 v[220:223], v146 offset:3072
	ds_read_b128 v[224:227], v146 offset:4096
	ds_read_b128 v[228:231], v146 offset:5120
	ds_read_b128 v[232:235], v146 offset:6144
	ds_read_b128 v[236:239], v146 offset:7168
	global_load_lds_dwordx4 v[142:143], off
	v_lshl_add_u64 v[142:143], s[18:19], 0, v[140:141]
	s_add_i32 m0, s27, 0xe000
	s_nop 0
	global_load_lds_dwordx4 v[142:143], off
	s_waitcnt vmcnt(8)
	s_waitcnt lgkmcnt(0)
	s_barrier
	s_waitcnt lgkmcnt(0)
	v_mfma_f32_16x16x32_bf16 v[126:129], v[148:151], v[208:211], v[126:129]
	v_mfma_f32_16x16x32_bf16 v[118:121], v[156:159], v[208:211], v[118:121]
	v_mfma_f32_16x16x32_bf16 v[110:113], v[148:151], v[216:219], v[110:113]
	v_mfma_f32_16x16x32_bf16 v[102:105], v[156:159], v[216:219], v[102:105]
	v_mfma_f32_16x16x32_bf16 v[94:97], v[148:151], v[224:227], v[94:97]
	v_mfma_f32_16x16x32_bf16 v[86:89], v[156:159], v[224:227], v[86:89]
	v_mfma_f32_16x16x32_bf16 v[78:81], v[148:151], v[232:235], v[78:81]
	v_mfma_f32_16x16x32_bf16 v[70:73], v[156:159], v[232:235], v[70:73]
	v_mfma_f32_16x16x32_bf16 v[126:129], v[152:155], v[212:215], v[126:129]
	v_mfma_f32_16x16x32_bf16 v[118:121], v[174:177], v[212:215], v[118:121]
	v_mfma_f32_16x16x32_bf16 v[110:113], v[152:155], v[220:223], v[110:113]
	v_mfma_f32_16x16x32_bf16 v[102:105], v[174:177], v[220:223], v[102:105]
	v_mfma_f32_16x16x32_bf16 v[94:97], v[152:155], v[228:231], v[94:97]
	v_mfma_f32_16x16x32_bf16 v[86:89], v[174:177], v[228:231], v[86:89]
	v_mfma_f32_16x16x32_bf16 v[78:81], v[152:155], v[236:239], v[78:81]
	v_mfma_f32_16x16x32_bf16 v[70:73], v[174:177], v[236:239], v[70:73]
	v_mfma_f32_16x16x32_bf16 v[122:125], v[178:181], v[208:211], v[122:125]
	v_mfma_f32_16x16x32_bf16 v[114:117], v[200:203], v[208:211], v[114:117]
	v_mfma_f32_16x16x32_bf16 v[106:109], v[178:181], v[216:219], v[106:109]
	v_mfma_f32_16x16x32_bf16 v[98:101], v[200:203], v[216:219], v[98:101]
	v_mfma_f32_16x16x32_bf16 v[90:93], v[178:181], v[224:227], v[90:93]
	v_mfma_f32_16x16x32_bf16 v[82:85], v[200:203], v[224:227], v[82:85]
	v_mfma_f32_16x16x32_bf16 v[74:77], v[178:181], v[232:235], v[74:77]
	v_mfma_f32_16x16x32_bf16 v[66:69], v[200:203], v[232:235], v[66:69]
	v_mfma_f32_16x16x32_bf16 v[122:125], v[182:185], v[212:215], v[122:125]
	v_mfma_f32_16x16x32_bf16 v[114:117], v[204:207], v[212:215], v[114:117]
	v_mfma_f32_16x16x32_bf16 v[106:109], v[182:185], v[220:223], v[106:109]
	v_mfma_f32_16x16x32_bf16 v[98:101], v[204:207], v[220:223], v[98:101]
	v_mfma_f32_16x16x32_bf16 v[90:93], v[182:185], v[228:231], v[90:93]
	v_mfma_f32_16x16x32_bf16 v[82:85], v[204:207], v[228:231], v[82:85]
	v_mfma_f32_16x16x32_bf16 v[74:77], v[182:185], v[236:239], v[74:77]
	v_mfma_f32_16x16x32_bf16 v[66:69], v[204:207], v[236:239], v[66:69]
	s_barrier
	s_add_i32 s45, s45, s26
	v_lshl_add_u64 v[142:143], s[20:21], 0, v[134:135]
	s_mov_b32 m0, s45
	ds_read_b128 v[208:211], v146 offset:16384
	ds_read_b128 v[212:215], v146 offset:17408
	ds_read_b128 v[216:219], v146 offset:18432
	ds_read_b128 v[220:223], v146 offset:19456
	ds_read_b128 v[224:227], v146 offset:20480
	ds_read_b128 v[228:231], v146 offset:21504
	ds_read_b128 v[232:235], v146 offset:22528
	ds_read_b128 v[236:239], v146 offset:23552
	global_load_lds_dwordx4 v[142:143], off
	s_add_i32 m0, s45, 0x2000
	s_add_u32 s46, s20, 0x80000
	v_lshl_add_u64 v[160:161], s[20:21], 0, v[130:131]
	s_addc_u32 s47, s21, 0
	s_add_i32 s45, s48, s26
	global_load_lds_dwordx4 v[160:161], off
	v_lshl_add_u64 v[240:241], s[46:47], 0, v[134:135]
	s_mov_b32 m0, s45
	v_lshl_add_u64 v[242:243], s[22:23], 0, v[132:133]
	global_load_lds_dwordx4 v[240:241], off
	v_lshl_add_u64 v[240:241], s[46:47], 0, v[130:131]
	s_add_i32 m0, s45, 0x2000
	s_nop 0
	global_load_lds_dwordx4 v[240:241], off
	v_lshl_add_u64 v[240:241], s[22:23], 0, v[136:137]
	s_mov_b32 m0, s27
	s_nop 0
	global_load_lds_dwordx4 v[240:241], off
	s_mov_b32 m0, s28
	s_nop 0
	global_load_lds_dwordx4 v[242:243], off
	s_waitcnt vmcnt(8)
	s_waitcnt lgkmcnt(0)
	s_barrier
	s_waitcnt lgkmcnt(0)
	v_mfma_f32_16x16x32_bf16 v[60:63], v[148:151], v[208:211], v[60:63]
	v_mfma_f32_16x16x32_bf16 v[52:55], v[156:159], v[208:211], v[52:55]
	v_mfma_f32_16x16x32_bf16 v[44:47], v[148:151], v[216:219], v[44:47]
	v_mfma_f32_16x16x32_bf16 v[36:39], v[156:159], v[216:219], v[36:39]
	v_mfma_f32_16x16x32_bf16 v[28:31], v[148:151], v[224:227], v[28:31]
	v_mfma_f32_16x16x32_bf16 v[20:23], v[156:159], v[224:227], v[20:23]
	v_mfma_f32_16x16x32_bf16 v[12:15], v[148:151], v[232:235], v[12:15]
	v_mfma_f32_16x16x32_bf16 v[4:7], v[156:159], v[232:235], v[4:7]
	v_mfma_f32_16x16x32_bf16 v[60:63], v[152:155], v[212:215], v[60:63]
	v_mfma_f32_16x16x32_bf16 v[52:55], v[174:177], v[212:215], v[52:55]
	v_mfma_f32_16x16x32_bf16 v[44:47], v[152:155], v[220:223], v[44:47]
	v_mfma_f32_16x16x32_bf16 v[36:39], v[174:177], v[220:223], v[36:39]
	v_mfma_f32_16x16x32_bf16 v[28:31], v[152:155], v[228:231], v[28:31]
	v_mfma_f32_16x16x32_bf16 v[20:23], v[174:177], v[228:231], v[20:23]
	v_mfma_f32_16x16x32_bf16 v[12:15], v[152:155], v[236:239], v[12:15]
	v_mfma_f32_16x16x32_bf16 v[4:7], v[174:177], v[236:239], v[4:7]
	v_mfma_f32_16x16x32_bf16 v[56:59], v[178:181], v[208:211], v[56:59]
	v_mfma_f32_16x16x32_bf16 v[48:51], v[200:203], v[208:211], v[48:51]
	v_mfma_f32_16x16x32_bf16 v[40:43], v[178:181], v[216:219], v[40:43]
	v_mfma_f32_16x16x32_bf16 v[32:35], v[200:203], v[216:219], v[32:35]
	v_mfma_f32_16x16x32_bf16 v[24:27], v[178:181], v[224:227], v[24:27]
	v_mfma_f32_16x16x32_bf16 v[16:19], v[200:203], v[224:227], v[16:19]
	v_mfma_f32_16x16x32_bf16 v[8:11], v[178:181], v[232:235], v[8:11]
	v_mfma_f32_16x16x32_bf16 v[0:3], v[200:203], v[232:235], v[0:3]
	v_mfma_f32_16x16x32_bf16 v[56:59], v[182:185], v[212:215], v[56:59]
	v_mfma_f32_16x16x32_bf16 v[48:51], v[204:207], v[212:215], v[48:51]
	v_mfma_f32_16x16x32_bf16 v[40:43], v[182:185], v[220:223], v[40:43]
	v_mfma_f32_16x16x32_bf16 v[32:35], v[204:207], v[220:223], v[32:35]
	v_mfma_f32_16x16x32_bf16 v[24:27], v[182:185], v[228:231], v[24:27]
	v_mfma_f32_16x16x32_bf16 v[16:19], v[204:207], v[228:231], v[16:19]
	v_mfma_f32_16x16x32_bf16 v[8:11], v[182:185], v[236:239], v[8:11]
	v_mfma_f32_16x16x32_bf16 v[0:3], v[204:207], v[236:239], v[0:3]
	s_barrier
	s_add_i32 s45, 0, 0x18000
	v_add_u32_e32 v147, s45, v145
	s_add_i32 s46, 0, 0x1c000
	ds_read_b128 v[148:151], v147
	ds_read_b128 v[152:155], v147 offset:1024
	ds_read_b128 v[156:159], v147 offset:2048
	ds_read_b128 v[174:177], v147 offset:3072
	v_add_u32_e32 v147, s46, v145
	ds_read_b128 v[178:181], v147
	ds_read_b128 v[182:185], v147 offset:1024
	ds_read_b128 v[200:203], v147 offset:2048
	ds_read_b128 v[204:207], v147 offset:3072
	s_add_u32 s22, s22, 0x80000
	s_addc_u32 s23, s23, 0
	s_mov_b32 m0, s29
	v_lshl_add_u64 v[244:245], s[22:23], 0, v[136:137]
	ds_read_b128 v[208:211], v146 offset:32768
	ds_read_b128 v[212:215], v146 offset:33792
	ds_read_b128 v[216:219], v146 offset:34816
	ds_read_b128 v[220:223], v146 offset:35840
	ds_read_b128 v[224:227], v146 offset:36864
	ds_read_b128 v[228:231], v146 offset:37888
	ds_read_b128 v[232:235], v146 offset:38912
	ds_read_b128 v[236:239], v146 offset:39936
	global_load_lds_dwordx4 v[244:245], off
	v_lshl_add_u64 v[244:245], s[22:23], 0, v[132:133]
	s_mov_b32 m0, s30
	s_nop 0
	global_load_lds_dwordx4 v[244:245], off
	s_waitcnt vmcnt(8)
	s_waitcnt lgkmcnt(0)
	s_barrier
	s_waitcnt lgkmcnt(0)
	v_mfma_f32_16x16x32_bf16 v[126:129], v[148:151], v[208:211], v[126:129]
	v_mfma_f32_16x16x32_bf16 v[118:121], v[156:159], v[208:211], v[118:121]
	v_mfma_f32_16x16x32_bf16 v[110:113], v[148:151], v[216:219], v[110:113]
	v_mfma_f32_16x16x32_bf16 v[102:105], v[156:159], v[216:219], v[102:105]
	v_mfma_f32_16x16x32_bf16 v[94:97], v[148:151], v[224:227], v[94:97]
	v_mfma_f32_16x16x32_bf16 v[86:89], v[156:159], v[224:227], v[86:89]
	v_mfma_f32_16x16x32_bf16 v[78:81], v[148:151], v[232:235], v[78:81]
	v_mfma_f32_16x16x32_bf16 v[70:73], v[156:159], v[232:235], v[70:73]
	v_mfma_f32_16x16x32_bf16 v[126:129], v[152:155], v[212:215], v[126:129]
	v_mfma_f32_16x16x32_bf16 v[118:121], v[174:177], v[212:215], v[118:121]
	v_mfma_f32_16x16x32_bf16 v[110:113], v[152:155], v[220:223], v[110:113]
	v_mfma_f32_16x16x32_bf16 v[102:105], v[174:177], v[220:223], v[102:105]
	v_mfma_f32_16x16x32_bf16 v[94:97], v[152:155], v[228:231], v[94:97]
	v_mfma_f32_16x16x32_bf16 v[86:89], v[174:177], v[228:231], v[86:89]
	v_mfma_f32_16x16x32_bf16 v[78:81], v[152:155], v[236:239], v[78:81]
	v_mfma_f32_16x16x32_bf16 v[70:73], v[174:177], v[236:239], v[70:73]
	v_mfma_f32_16x16x32_bf16 v[122:125], v[178:181], v[208:211], v[122:125]
	v_mfma_f32_16x16x32_bf16 v[114:117], v[200:203], v[208:211], v[114:117]
	v_mfma_f32_16x16x32_bf16 v[106:109], v[178:181], v[216:219], v[106:109]
	v_mfma_f32_16x16x32_bf16 v[98:101], v[200:203], v[216:219], v[98:101]
	v_mfma_f32_16x16x32_bf16 v[90:93], v[178:181], v[224:227], v[90:93]
	v_mfma_f32_16x16x32_bf16 v[82:85], v[200:203], v[224:227], v[82:85]
	v_mfma_f32_16x16x32_bf16 v[74:77], v[178:181], v[232:235], v[74:77]
	v_mfma_f32_16x16x32_bf16 v[66:69], v[200:203], v[232:235], v[66:69]
	v_mfma_f32_16x16x32_bf16 v[122:125], v[182:185], v[212:215], v[122:125]
	v_mfma_f32_16x16x32_bf16 v[114:117], v[204:207], v[212:215], v[114:117]
	v_mfma_f32_16x16x32_bf16 v[106:109], v[182:185], v[220:223], v[106:109]
	v_mfma_f32_16x16x32_bf16 v[98:101], v[204:207], v[220:223], v[98:101]
	v_mfma_f32_16x16x32_bf16 v[90:93], v[182:185], v[228:231], v[90:93]
	v_mfma_f32_16x16x32_bf16 v[82:85], v[204:207], v[228:231], v[82:85]
	v_mfma_f32_16x16x32_bf16 v[74:77], v[182:185], v[236:239], v[74:77]
	v_mfma_f32_16x16x32_bf16 v[66:69], v[204:207], v[236:239], v[66:69]
	s_barrier
	s_add_i32 s22, s45, s26
	v_lshl_add_u64 v[142:143], v[142:143], 0, s[94:95]
	s_mov_b32 m0, s22
	ds_read_b128 v[208:211], v146 offset:49152
	ds_read_b128 v[212:215], v146 offset:50176
	ds_read_b128 v[216:219], v146 offset:51200
	ds_read_b128 v[220:223], v146 offset:52224
	ds_read_b128 v[224:227], v146 offset:53248
	ds_read_b128 v[228:231], v146 offset:54272
	ds_read_b128 v[232:235], v146 offset:55296
	ds_read_b128 v[236:239], v146 offset:56320
	global_load_lds_dwordx4 v[142:143], off
	s_add_i32 m0, s22, 0x2000
	s_add_u32 s20, s20, 0x80080
	v_lshl_add_u64 v[142:143], v[160:161], 0, s[94:95]
	s_addc_u32 s21, s21, 0
	s_add_i32 s22, s46, s26
	global_load_lds_dwordx4 v[142:143], off
	v_lshl_add_u64 v[142:143], s[20:21], 0, v[134:135]
	s_mov_b32 m0, s22
	s_nop 0
	global_load_lds_dwordx4 v[142:143], off
	v_lshl_add_u64 v[142:143], s[20:21], 0, v[130:131]
	s_add_i32 m0, s22, 0x2000
	s_nop 0
	global_load_lds_dwordx4 v[142:143], off
	v_lshl_add_u64 v[142:143], v[240:241], 0, s[94:95]
	s_mov_b32 m0, s31
	s_nop 0
	global_load_lds_dwordx4 v[142:143], off
	v_lshl_add_u64 v[142:143], v[242:243], 0, s[94:95]
	s_mov_b32 m0, s34
	s_nop 0
	global_load_lds_dwordx4 v[142:143], off
	s_waitcnt vmcnt(8)
	s_waitcnt lgkmcnt(0)
	s_barrier
	s_waitcnt lgkmcnt(0)
	v_mfma_f32_16x16x32_bf16 v[60:63], v[148:151], v[208:211], v[60:63]
	v_mfma_f32_16x16x32_bf16 v[52:55], v[156:159], v[208:211], v[52:55]
	v_mfma_f32_16x16x32_bf16 v[44:47], v[148:151], v[216:219], v[44:47]
	v_mfma_f32_16x16x32_bf16 v[36:39], v[156:159], v[216:219], v[36:39]
	v_mfma_f32_16x16x32_bf16 v[28:31], v[148:151], v[224:227], v[28:31]
	v_mfma_f32_16x16x32_bf16 v[20:23], v[156:159], v[224:227], v[20:23]
	v_mfma_f32_16x16x32_bf16 v[12:15], v[148:151], v[232:235], v[12:15]
	v_mfma_f32_16x16x32_bf16 v[4:7], v[156:159], v[232:235], v[4:7]
	v_mfma_f32_16x16x32_bf16 v[60:63], v[152:155], v[212:215], v[60:63]
	v_mfma_f32_16x16x32_bf16 v[52:55], v[174:177], v[212:215], v[52:55]
	v_mfma_f32_16x16x32_bf16 v[44:47], v[152:155], v[220:223], v[44:47]
	v_mfma_f32_16x16x32_bf16 v[36:39], v[174:177], v[220:223], v[36:39]
	v_mfma_f32_16x16x32_bf16 v[28:31], v[152:155], v[228:231], v[28:31]
	v_mfma_f32_16x16x32_bf16 v[20:23], v[174:177], v[228:231], v[20:23]
	v_mfma_f32_16x16x32_bf16 v[12:15], v[152:155], v[236:239], v[12:15]
	v_mfma_f32_16x16x32_bf16 v[4:7], v[174:177], v[236:239], v[4:7]
	v_mfma_f32_16x16x32_bf16 v[56:59], v[178:181], v[208:211], v[56:59]
	v_mfma_f32_16x16x32_bf16 v[48:51], v[200:203], v[208:211], v[48:51]
	v_mfma_f32_16x16x32_bf16 v[40:43], v[178:181], v[216:219], v[40:43]
	v_mfma_f32_16x16x32_bf16 v[32:35], v[200:203], v[216:219], v[32:35]
	v_mfma_f32_16x16x32_bf16 v[24:27], v[178:181], v[224:227], v[24:27]
	v_mfma_f32_16x16x32_bf16 v[16:19], v[200:203], v[224:227], v[16:19]
	v_mfma_f32_16x16x32_bf16 v[8:11], v[178:181], v[232:235], v[8:11]
	v_mfma_f32_16x16x32_bf16 v[0:3], v[200:203], v[232:235], v[0:3]
	v_mfma_f32_16x16x32_bf16 v[56:59], v[182:185], v[212:215], v[56:59]
	v_mfma_f32_16x16x32_bf16 v[48:51], v[204:207], v[212:215], v[48:51]
	v_mfma_f32_16x16x32_bf16 v[40:43], v[182:185], v[220:223], v[40:43]
	v_mfma_f32_16x16x32_bf16 v[32:35], v[204:207], v[220:223], v[32:35]
	v_mfma_f32_16x16x32_bf16 v[24:27], v[182:185], v[228:231], v[24:27]
	v_mfma_f32_16x16x32_bf16 v[16:19], v[204:207], v[228:231], v[16:19]
	v_mfma_f32_16x16x32_bf16 v[8:11], v[182:185], v[236:239], v[8:11]
	v_mfma_f32_16x16x32_bf16 v[0:3], v[204:207], v[236:239], v[0:3]
	s_barrier
	s_add_i32 s44, s44, 2
	s_add_u32 s18, s18, 0x100
	s_addc_u32 s19, s19, 0
	s_add_u32 s42, s42, 0x100
	s_addc_u32 s43, s43, 0
	s_cmp_gt_u32 s44, 29
	s_cbranch_scc0 .LBB0_93
	s_setprio 0
	s_and_b64 vcc, exec, s[8:9]
	s_cbranch_vccz .LBB0_96
	s_barrier

.LBB0_121:
	s_ashr_i32 s13, s12, 31
	s_lshl_b64 s[14:15], s[12:13], 20
	v_readlane_b32 s16, v254, 57
	v_readlane_b32 s17, v254, 58
	s_add_u32 s14, s16, s14
	s_addc_u32 s15, s17, s15
	s_and_b64 s[16:17], s[38:39], exec
	s_cselect_b32 s13, s15, s21
	s_cselect_b32 s36, s14, s20
	s_ashr_i32 s11, s10, 31
	s_lshl_b64 s[16:17], s[10:11], 20
	s_add_u32 s16, s24, s16
	s_addc_u32 s17, s25, s17
	s_and_b64 s[22:23], s[38:39], exec
	s_cselect_b32 s11, s17, s19
	s_cselect_b32 s40, s16, s18
	s_add_u32 s41, s18, 0x100
	s_addc_u32 s42, s19, 0
	s_add_u32 s18, s20, 0x80080
	v_mov_b32_e32 v0, 0
	s_addc_u32 s19, s21, 0
	s_mov_b32 s43, -2
	v_mov_b32_e32 v1, v0
	v_mov_b32_e32 v2, v0
	v_mov_b32_e32 v3, v0
	v_mov_b32_e32 v4, v0
	v_mov_b32_e32 v5, v0
	v_mov_b32_e32 v6, v0
	v_mov_b32_e32 v7, v0
	v_mov_b32_e32 v8, v0
	v_mov_b32_e32 v9, v0
	v_mov_b32_e32 v10, v0
	v_mov_b32_e32 v11, v0
	v_mov_b32_e32 v12, v0
	v_mov_b32_e32 v13, v0
	v_mov_b32_e32 v14, v0
	v_mov_b32_e32 v15, v0
	v_mov_b32_e32 v32, v0
	v_mov_b32_e32 v33, v0
	v_mov_b32_e32 v34, v0
	v_mov_b32_e32 v35, v0
	v_mov_b32_e32 v36, v0
	v_mov_b32_e32 v37, v0
	v_mov_b32_e32 v38, v0
	v_mov_b32_e32 v39, v0
	v_mov_b32_e32 v48, v0
	v_mov_b32_e32 v49, v0
	v_mov_b32_e32 v50, v0
	v_mov_b32_e32 v51, v0
	v_mov_b32_e32 v52, v0
	v_mov_b32_e32 v53, v0
	v_mov_b32_e32 v54, v0
	v_mov_b32_e32 v55, v0
	v_mov_b32_e32 v16, v0
	v_mov_b32_e32 v17, v0
	v_mov_b32_e32 v18, v0
	v_mov_b32_e32 v19, v0
	v_mov_b32_e32 v20, v0
	v_mov_b32_e32 v21, v0
	v_mov_b32_e32 v22, v0
	v_mov_b32_e32 v23, v0
	v_mov_b32_e32 v24, v0
	v_mov_b32_e32 v25, v0
	v_mov_b32_e32 v26, v0
	v_mov_b32_e32 v27, v0
	v_mov_b32_e32 v28, v0
	v_mov_b32_e32 v29, v0
	v_mov_b32_e32 v30, v0
	v_mov_b32_e32 v31, v0
	v_mov_b32_e32 v40, v0
	v_mov_b32_e32 v41, v0
	v_mov_b32_e32 v42, v0
	v_mov_b32_e32 v43, v0
	v_mov_b32_e32 v44, v0
	v_mov_b32_e32 v45, v0
	v_mov_b32_e32 v46, v0
	v_mov_b32_e32 v47, v0
	v_mov_b32_e32 v56, v0
	v_mov_b32_e32 v57, v0
	v_mov_b32_e32 v58, v0
	v_mov_b32_e32 v59, v0
	v_mov_b32_e32 v60, v0
	v_mov_b32_e32 v61, v0
	v_mov_b32_e32 v62, v0
	v_mov_b32_e32 v63, v0
	v_mov_b32_e32 v66, v0
	v_mov_b32_e32 v67, v0
	v_mov_b32_e32 v68, v0
	v_mov_b32_e32 v69, v0
	v_mov_b32_e32 v70, v0
	v_mov_b32_e32 v71, v0
	v_mov_b32_e32 v72, v0
	v_mov_b32_e32 v73, v0
	v_mov_b32_e32 v82, v0
	v_mov_b32_e32 v83, v0
	v_mov_b32_e32 v84, v0
	v_mov_b32_e32 v85, v0
	v_mov_b32_e32 v86, v0
	v_mov_b32_e32 v87, v0
	v_mov_b32_e32 v88, v0
	v_mov_b32_e32 v89, v0
	v_mov_b32_e32 v98, v0
	v_mov_b32_e32 v99, v0
	v_mov_b32_e32 v100, v0
	v_mov_b32_e32 v101, v0
	v_mov_b32_e32 v102, v0
	v_mov_b32_e32 v103, v0
	v_mov_b32_e32 v104, v0
	v_mov_b32_e32 v105, v0
	v_mov_b32_e32 v114, v0
	v_mov_b32_e32 v115, v0
	v_mov_b32_e32 v116, v0
	v_mov_b32_e32 v117, v0
	v_mov_b32_e32 v118, v0
	v_mov_b32_e32 v119, v0
	v_mov_b32_e32 v120, v0
	v_mov_b32_e32 v121, v0
	v_mov_b32_e32 v74, v0
	v_mov_b32_e32 v75, v0
	v_mov_b32_e32 v76, v0
	v_mov_b32_e32 v77, v0
	v_mov_b32_e32 v78, v0
	v_mov_b32_e32 v79, v0
	v_mov_b32_e32 v80, v0
	v_mov_b32_e32 v81, v0
	v_mov_b32_e32 v90, v0
	v_mov_b32_e32 v91, v0
	v_mov_b32_e32 v92, v0
	v_mov_b32_e32 v93, v0
	v_mov_b32_e32 v94, v0
	v_mov_b32_e32 v95, v0
	v_mov_b32_e32 v96, v0
	v_mov_b32_e32 v97, v0
	v_mov_b32_e32 v106, v0
	v_mov_b32_e32 v107, v0
	v_mov_b32_e32 v108, v0
	v_mov_b32_e32 v109, v0
	v_mov_b32_e32 v110, v0
	v_mov_b32_e32 v111, v0
	v_mov_b32_e32 v112, v0
	v_mov_b32_e32 v113, v0
	v_mov_b32_e32 v122, v0
	v_mov_b32_e32 v123, v0
	v_mov_b32_e32 v124, v0
	v_mov_b32_e32 v125, v0
	v_mov_b32_e32 v126, v0
	v_mov_b32_e32 v127, v0
	v_mov_b32_e32 v128, v0
	v_mov_b32_e32 v129, v0
	v_readfirstlane_b32 s98, v186
	s_cmpk_lt_u32 s98, 0x100
	s_cbranch_scc1 .Lgp_skip2
	s_setprio 1
.Lgp_skip2:
.LBB0_122:
	s_add_u32 s20, s18, 0xfff80080
	s_addc_u32 s21, s19, -1
	s_add_i32 s44, 0, 0x10000
	s_cmp_eq_u32 s43, 28
	s_cselect_b32 s23, s13, s21
	s_cselect_b32 s22, s36, s20
	s_cselect_b32 s21, s11, s42
	s_cselect_b32 s20, s40, s41
	s_add_i32 s46, 0, 0x14000
	v_add_u32_e32 v156, s44, v146
	v_add_u32_e32 v160, s46, v146
	ds_read_b128 v[142:145], v156
	ds_read_b128 v[148:151], v156 offset:1024
	ds_read_b128 v[152:155], v156 offset:2048
	ds_read_b128 v[156:159], v156 offset:3072
	ds_read_b128 v[174:177], v160
	ds_read_b128 v[178:181], v160 offset:1024
	ds_read_b128 v[182:185], v160 offset:2048
	ds_read_b128 v[200:203], v160 offset:3072
	v_lshl_add_u64 v[160:161], s[18:19], 0, v[138:139]
	s_add_i32 m0, s27, 0xc000
	ds_read_b128 v[204:207], v147
	ds_read_b128 v[208:211], v147 offset:1024
	ds_read_b128 v[212:215], v147 offset:2048
	ds_read_b128 v[216:219], v147 offset:3072
	ds_read_b128 v[220:223], v147 offset:4096
	ds_read_b128 v[224:227], v147 offset:5120
	ds_read_b128 v[228:231], v147 offset:6144
	ds_read_b128 v[232:235], v147 offset:7168
	global_load_lds_dwordx4 v[160:161], off
	v_lshl_add_u64 v[160:161], s[18:19], 0, v[140:141]
	s_add_i32 m0, s27, 0xe000
	s_nop 0
	global_load_lds_dwordx4 v[160:161], off
	s_waitcnt vmcnt(8)
	s_waitcnt lgkmcnt(0)
	s_barrier
	s_waitcnt lgkmcnt(0)
	v_mfma_f32_16x16x32_bf16 v[126:129], v[142:145], v[204:207], v[126:129]
	v_mfma_f32_16x16x32_bf16 v[122:125], v[152:155], v[204:207], v[122:125]
	v_mfma_f32_16x16x32_bf16 v[110:113], v[142:145], v[212:215], v[110:113]
	v_mfma_f32_16x16x32_bf16 v[106:109], v[152:155], v[212:215], v[106:109]
	v_mfma_f32_16x16x32_bf16 v[94:97], v[142:145], v[220:223], v[94:97]
	v_mfma_f32_16x16x32_bf16 v[90:93], v[152:155], v[220:223], v[90:93]
	v_mfma_f32_16x16x32_bf16 v[78:81], v[142:145], v[228:231], v[78:81]
	v_mfma_f32_16x16x32_bf16 v[74:77], v[152:155], v[228:231], v[74:77]
	v_mfma_f32_16x16x32_bf16 v[126:129], v[148:151], v[208:211], v[126:129]
	v_mfma_f32_16x16x32_bf16 v[122:125], v[156:159], v[208:211], v[122:125]
	v_mfma_f32_16x16x32_bf16 v[110:113], v[148:151], v[216:219], v[110:113]
	v_mfma_f32_16x16x32_bf16 v[106:109], v[156:159], v[216:219], v[106:109]
	v_mfma_f32_16x16x32_bf16 v[94:97], v[148:151], v[224:227], v[94:97]
	v_mfma_f32_16x16x32_bf16 v[90:93], v[156:159], v[224:227], v[90:93]
	v_mfma_f32_16x16x32_bf16 v[78:81], v[148:151], v[232:235], v[78:81]
	v_mfma_f32_16x16x32_bf16 v[74:77], v[156:159], v[232:235], v[74:77]
	v_mfma_f32_16x16x32_bf16 v[118:121], v[174:177], v[204:207], v[118:121]
	v_mfma_f32_16x16x32_bf16 v[114:117], v[182:185], v[204:207], v[114:117]
	v_mfma_f32_16x16x32_bf16 v[102:105], v[174:177], v[212:215], v[102:105]
	v_mfma_f32_16x16x32_bf16 v[98:101], v[182:185], v[212:215], v[98:101]
	v_mfma_f32_16x16x32_bf16 v[86:89], v[174:177], v[220:223], v[86:89]
	v_mfma_f32_16x16x32_bf16 v[82:85], v[182:185], v[220:223], v[82:85]
	v_mfma_f32_16x16x32_bf16 v[70:73], v[174:177], v[228:231], v[70:73]
	v_mfma_f32_16x16x32_bf16 v[66:69], v[182:185], v[228:231], v[66:69]
	v_mfma_f32_16x16x32_bf16 v[118:121], v[178:181], v[208:211], v[118:121]
	v_mfma_f32_16x16x32_bf16 v[114:117], v[200:203], v[208:211], v[114:117]
	v_mfma_f32_16x16x32_bf16 v[102:105], v[178:181], v[216:219], v[102:105]
	v_mfma_f32_16x16x32_bf16 v[98:101], v[200:203], v[216:219], v[98:101]
	v_mfma_f32_16x16x32_bf16 v[86:89], v[178:181], v[224:227], v[86:89]
	v_mfma_f32_16x16x32_bf16 v[82:85], v[200:203], v[224:227], v[82:85]
	v_mfma_f32_16x16x32_bf16 v[70:73], v[178:181], v[232:235], v[70:73]
	v_mfma_f32_16x16x32_bf16 v[66:69], v[200:203], v[232:235], v[66:69]
	s_barrier
	s_add_i32 s44, s44, s26
	v_lshl_add_u64 v[160:161], s[20:21], 0, v[64:65]
	s_mov_b32 m0, s44
	ds_read_b128 v[204:207], v147 offset:16384
	ds_read_b128 v[208:211], v147 offset:17408
	ds_read_b128 v[212:215], v147 offset:18432
	ds_read_b128 v[216:219], v147 offset:19456
	ds_read_b128 v[220:223], v147 offset:20480
	ds_read_b128 v[224:227], v147 offset:21504
	ds_read_b128 v[228:231], v147 offset:22528
	ds_read_b128 v[232:235], v147 offset:23552
	global_load_lds_dwordx4 v[160:161], off
	s_add_i32 m0, s44, 0x2000
	s_add_u32 s44, s20, 0x80000
	v_lshl_add_u64 v[236:237], s[20:21], 0, v[130:131]
	s_addc_u32 s45, s21, 0
	s_add_i32 s46, s46, s26
	global_load_lds_dwordx4 v[236:237], off
	v_lshl_add_u64 v[238:239], s[44:45], 0, v[64:65]
	s_mov_b32 m0, s46
	v_lshl_add_u64 v[240:241], s[22:23], 0, v[132:133]
	global_load_lds_dwordx4 v[238:239], off
	v_lshl_add_u64 v[238:239], s[44:45], 0, v[130:131]
	s_add_i32 m0, s46, 0x2000
	s_nop 0
	global_load_lds_dwordx4 v[238:239], off
	v_lshl_add_u64 v[238:239], s[22:23], 0, v[134:135]
	s_mov_b32 m0, s27
	s_nop 0
	global_load_lds_dwordx4 v[238:239], off
	s_mov_b32 m0, s28
	s_nop 0
	global_load_lds_dwordx4 v[240:241], off
	s_waitcnt vmcnt(8)
	s_waitcnt lgkmcnt(0)
	s_barrier
	s_waitcnt lgkmcnt(0)
	v_mfma_f32_16x16x32_bf16 v[60:63], v[142:145], v[204:207], v[60:63]
	v_mfma_f32_16x16x32_bf16 v[56:59], v[152:155], v[204:207], v[56:59]
	v_mfma_f32_16x16x32_bf16 v[44:47], v[142:145], v[212:215], v[44:47]
	v_mfma_f32_16x16x32_bf16 v[40:43], v[152:155], v[212:215], v[40:43]
	v_mfma_f32_16x16x32_bf16 v[28:31], v[142:145], v[220:223], v[28:31]
	v_mfma_f32_16x16x32_bf16 v[24:27], v[152:155], v[220:223], v[24:27]
	v_mfma_f32_16x16x32_bf16 v[20:23], v[142:145], v[228:231], v[20:23]
	v_mfma_f32_16x16x32_bf16 v[16:19], v[152:155], v[228:231], v[16:19]
	v_mfma_f32_16x16x32_bf16 v[60:63], v[148:151], v[208:211], v[60:63]
	v_mfma_f32_16x16x32_bf16 v[56:59], v[156:159], v[208:211], v[56:59]
	v_mfma_f32_16x16x32_bf16 v[44:47], v[148:151], v[216:219], v[44:47]
	v_mfma_f32_16x16x32_bf16 v[40:43], v[156:159], v[216:219], v[40:43]
	v_mfma_f32_16x16x32_bf16 v[28:31], v[148:151], v[224:227], v[28:31]
	v_mfma_f32_16x16x32_bf16 v[24:27], v[156:159], v[224:227], v[24:27]
	v_mfma_f32_16x16x32_bf16 v[20:23], v[148:151], v[232:235], v[20:23]
	v_mfma_f32_16x16x32_bf16 v[16:19], v[156:159], v[232:235], v[16:19]
	v_mfma_f32_16x16x32_bf16 v[52:55], v[174:177], v[204:207], v[52:55]
	v_mfma_f32_16x16x32_bf16 v[48:51], v[182:185], v[204:207], v[48:51]
	v_mfma_f32_16x16x32_bf16 v[36:39], v[174:177], v[212:215], v[36:39]
	v_mfma_f32_16x16x32_bf16 v[32:35], v[182:185], v[212:215], v[32:35]
	v_mfma_f32_16x16x32_bf16 v[12:15], v[174:177], v[220:223], v[12:15]
	v_mfma_f32_16x16x32_bf16 v[8:11], v[182:185], v[220:223], v[8:11]
	v_mfma_f32_16x16x32_bf16 v[4:7], v[174:177], v[228:231], v[4:7]
	v_mfma_f32_16x16x32_bf16 v[0:3], v[182:185], v[228:231], v[0:3]
	v_mfma_f32_16x16x32_bf16 v[52:55], v[178:181], v[208:211], v[52:55]
	v_mfma_f32_16x16x32_bf16 v[48:51], v[200:203], v[208:211], v[48:51]
	v_mfma_f32_16x16x32_bf16 v[36:39], v[178:181], v[216:219], v[36:39]
	v_mfma_f32_16x16x32_bf16 v[32:35], v[200:203], v[216:219], v[32:35]
	v_mfma_f32_16x16x32_bf16 v[12:15], v[178:181], v[224:227], v[12:15]
	v_mfma_f32_16x16x32_bf16 v[8:11], v[200:203], v[224:227], v[8:11]
	v_mfma_f32_16x16x32_bf16 v[4:7], v[178:181], v[232:235], v[4:7]
	v_mfma_f32_16x16x32_bf16 v[0:3], v[200:203], v[232:235], v[0:3]
	s_barrier
	s_add_i32 s44, 0, 0x18000
	s_add_i32 s45, 0, 0x1c000
	v_add_u32_e32 v156, s44, v146
	v_add_u32_e32 v199, s45, v146
	ds_read_b128 v[142:145], v156
	ds_read_b128 v[148:151], v156 offset:1024
	ds_read_b128 v[152:155], v156 offset:2048
	ds_read_b128 v[156:159], v156 offset:3072
	ds_read_b128 v[174:177], v199
	ds_read_b128 v[178:181], v199 offset:1024
	ds_read_b128 v[182:185], v199 offset:2048
	ds_read_b128 v[200:203], v199 offset:3072
	s_add_u32 s22, s22, 0x80000
	s_addc_u32 s23, s23, 0
	s_mov_b32 m0, s29
	v_lshl_add_u64 v[242:243], s[22:23], 0, v[134:135]
	ds_read_b128 v[204:207], v147 offset:32768
	ds_read_b128 v[208:211], v147 offset:33792
	ds_read_b128 v[212:215], v147 offset:34816
	ds_read_b128 v[216:219], v147 offset:35840
	ds_read_b128 v[220:223], v147 offset:36864
	ds_read_b128 v[224:227], v147 offset:37888
	ds_read_b128 v[228:231], v147 offset:38912
	ds_read_b128 v[232:235], v147 offset:39936
	global_load_lds_dwordx4 v[242:243], off
	v_lshl_add_u64 v[242:243], s[22:23], 0, v[132:133]
	s_mov_b32 m0, s30
	s_nop 0
	global_load_lds_dwordx4 v[242:243], off
	s_waitcnt vmcnt(8)
	s_waitcnt lgkmcnt(0)
	s_barrier
	s_waitcnt lgkmcnt(0)
	v_mfma_f32_16x16x32_bf16 v[126:129], v[142:145], v[204:207], v[126:129]
	v_mfma_f32_16x16x32_bf16 v[122:125], v[152:155], v[204:207], v[122:125]
	v_mfma_f32_16x16x32_bf16 v[110:113], v[142:145], v[212:215], v[110:113]
	v_mfma_f32_16x16x32_bf16 v[106:109], v[152:155], v[212:215], v[106:109]
	v_mfma_f32_16x16x32_bf16 v[94:97], v[142:145], v[220:223], v[94:97]
	v_mfma_f32_16x16x32_bf16 v[90:93], v[152:155], v[220:223], v[90:93]
	v_mfma_f32_16x16x32_bf16 v[78:81], v[142:145], v[228:231], v[78:81]
	v_mfma_f32_16x16x32_bf16 v[74:77], v[152:155], v[228:231], v[74:77]
	v_mfma_f32_16x16x32_bf16 v[126:129], v[148:151], v[208:211], v[126:129]
	v_mfma_f32_16x16x32_bf16 v[122:125], v[156:159], v[208:211], v[122:125]
	v_mfma_f32_16x16x32_bf16 v[110:113], v[148:151], v[216:219], v[110:113]
	v_mfma_f32_16x16x32_bf16 v[106:109], v[156:159], v[216:219], v[106:109]
	v_mfma_f32_16x16x32_bf16 v[94:97], v[148:151], v[224:227], v[94:97]
	v_mfma_f32_16x16x32_bf16 v[90:93], v[156:159], v[224:227], v[90:93]
	v_mfma_f32_16x16x32_bf16 v[78:81], v[148:151], v[232:235], v[78:81]
	v_mfma_f32_16x16x32_bf16 v[74:77], v[156:159], v[232:235], v[74:77]
	v_mfma_f32_16x16x32_bf16 v[118:121], v[174:177], v[204:207], v[118:121]
	v_mfma_f32_16x16x32_bf16 v[114:117], v[182:185], v[204:207], v[114:117]
	v_mfma_f32_16x16x32_bf16 v[102:105], v[174:177], v[212:215], v[102:105]
	v_mfma_f32_16x16x32_bf16 v[98:101], v[182:185], v[212:215], v[98:101]
	v_mfma_f32_16x16x32_bf16 v[86:89], v[174:177], v[220:223], v[86:89]
	v_mfma_f32_16x16x32_bf16 v[82:85], v[182:185], v[220:223], v[82:85]
	v_mfma_f32_16x16x32_bf16 v[70:73], v[174:177], v[228:231], v[70:73]
	v_mfma_f32_16x16x32_bf16 v[66:69], v[182:185], v[228:231], v[66:69]
	v_mfma_f32_16x16x32_bf16 v[118:121], v[178:181], v[208:211], v[118:121]
	v_mfma_f32_16x16x32_bf16 v[114:117], v[200:203], v[208:211], v[114:117]
	v_mfma_f32_16x16x32_bf16 v[102:105], v[178:181], v[216:219], v[102:105]
	v_mfma_f32_16x16x32_bf16 v[98:101], v[200:203], v[216:219], v[98:101]
	v_mfma_f32_16x16x32_bf16 v[86:89], v[178:181], v[224:227], v[86:89]
	v_mfma_f32_16x16x32_bf16 v[82:85], v[200:203], v[224:227], v[82:85]
	v_mfma_f32_16x16x32_bf16 v[70:73], v[178:181], v[232:235], v[70:73]
	v_mfma_f32_16x16x32_bf16 v[66:69], v[200:203], v[232:235], v[66:69]
	s_barrier
	s_add_i32 s22, s44, s26
	v_lshl_add_u64 v[160:161], v[160:161], 0, s[94:95]
	s_mov_b32 m0, s22
	ds_read_b128 v[204:207], v147 offset:49152
	ds_read_b128 v[208:211], v147 offset:50176
	ds_read_b128 v[212:215], v147 offset:51200
	ds_read_b128 v[216:219], v147 offset:52224
	ds_read_b128 v[220:223], v147 offset:53248
	ds_read_b128 v[224:227], v147 offset:54272
	ds_read_b128 v[228:231], v147 offset:55296
	ds_read_b128 v[232:235], v147 offset:56320
	global_load_lds_dwordx4 v[160:161], off
	s_add_i32 m0, s22, 0x2000
	s_add_u32 s20, s20, 0x80080
	v_lshl_add_u64 v[160:161], v[236:237], 0, s[94:95]
	s_addc_u32 s21, s21, 0
	s_add_i32 s22, s45, s26
	global_load_lds_dwordx4 v[160:161], off
	v_lshl_add_u64 v[160:161], s[20:21], 0, v[64:65]
	s_mov_b32 m0, s22
	s_nop 0
	global_load_lds_dwordx4 v[160:161], off
	v_lshl_add_u64 v[160:161], s[20:21], 0, v[130:131]
	s_add_i32 m0, s22, 0x2000
	s_nop 0
	global_load_lds_dwordx4 v[160:161], off
	v_lshl_add_u64 v[160:161], v[238:239], 0, s[94:95]
	s_mov_b32 m0, s31
	s_nop 0
	global_load_lds_dwordx4 v[160:161], off
	v_lshl_add_u64 v[160:161], v[240:241], 0, s[94:95]
	s_mov_b32 m0, s34
	s_nop 0
	global_load_lds_dwordx4 v[160:161], off
	s_waitcnt vmcnt(8)
	s_waitcnt lgkmcnt(0)
	s_barrier
	s_waitcnt lgkmcnt(0)
	v_mfma_f32_16x16x32_bf16 v[60:63], v[142:145], v[204:207], v[60:63]
	v_mfma_f32_16x16x32_bf16 v[56:59], v[152:155], v[204:207], v[56:59]
	v_mfma_f32_16x16x32_bf16 v[44:47], v[142:145], v[212:215], v[44:47]
	v_mfma_f32_16x16x32_bf16 v[40:43], v[152:155], v[212:215], v[40:43]
	v_mfma_f32_16x16x32_bf16 v[28:31], v[142:145], v[220:223], v[28:31]
	v_mfma_f32_16x16x32_bf16 v[24:27], v[152:155], v[220:223], v[24:27]
	v_mfma_f32_16x16x32_bf16 v[20:23], v[142:145], v[228:231], v[20:23]
	v_mfma_f32_16x16x32_bf16 v[16:19], v[152:155], v[228:231], v[16:19]
	v_mfma_f32_16x16x32_bf16 v[60:63], v[148:151], v[208:211], v[60:63]
	v_mfma_f32_16x16x32_bf16 v[56:59], v[156:159], v[208:211], v[56:59]
	v_mfma_f32_16x16x32_bf16 v[44:47], v[148:151], v[216:219], v[44:47]
	v_mfma_f32_16x16x32_bf16 v[40:43], v[156:159], v[216:219], v[40:43]
	v_mfma_f32_16x16x32_bf16 v[28:31], v[148:151], v[224:227], v[28:31]
	v_mfma_f32_16x16x32_bf16 v[24:27], v[156:159], v[224:227], v[24:27]
	v_mfma_f32_16x16x32_bf16 v[20:23], v[148:151], v[232:235], v[20:23]
	v_mfma_f32_16x16x32_bf16 v[16:19], v[156:159], v[232:235], v[16:19]
	v_mfma_f32_16x16x32_bf16 v[52:55], v[174:177], v[204:207], v[52:55]
	v_mfma_f32_16x16x32_bf16 v[48:51], v[182:185], v[204:207], v[48:51]
	v_mfma_f32_16x16x32_bf16 v[36:39], v[174:177], v[212:215], v[36:39]
	v_mfma_f32_16x16x32_bf16 v[32:35], v[182:185], v[212:215], v[32:35]
	v_mfma_f32_16x16x32_bf16 v[12:15], v[174:177], v[220:223], v[12:15]
	v_mfma_f32_16x16x32_bf16 v[8:11], v[182:185], v[220:223], v[8:11]
	v_mfma_f32_16x16x32_bf16 v[4:7], v[174:177], v[228:231], v[4:7]
	v_mfma_f32_16x16x32_bf16 v[0:3], v[182:185], v[228:231], v[0:3]
	v_mfma_f32_16x16x32_bf16 v[52:55], v[178:181], v[208:211], v[52:55]
	v_mfma_f32_16x16x32_bf16 v[48:51], v[200:203], v[208:211], v[48:51]
	v_mfma_f32_16x16x32_bf16 v[36:39], v[178:181], v[216:219], v[36:39]
	v_mfma_f32_16x16x32_bf16 v[32:35], v[200:203], v[216:219], v[32:35]
	v_mfma_f32_16x16x32_bf16 v[12:15], v[178:181], v[224:227], v[12:15]
	v_mfma_f32_16x16x32_bf16 v[8:11], v[200:203], v[224:227], v[8:11]
	v_mfma_f32_16x16x32_bf16 v[4:7], v[178:181], v[232:235], v[4:7]
	v_mfma_f32_16x16x32_bf16 v[0:3], v[200:203], v[232:235], v[0:3]
	s_barrier
	s_add_i32 s43, s43, 2
	s_add_u32 s41, s41, 0x100
	s_addc_u32 s42, s42, 0
	s_add_u32 s18, s18, 0x100
	s_addc_u32 s19, s19, 0
	s_cmp_gt_u32 s43, 29
	s_cbranch_scc0 .LBB0_122
	s_setprio 0
	s_and_b64 vcc, exec, s[8:9]
	s_cbranch_vccz .LBB0_125
	s_barrier

.LBB0_396:
	s_ashr_i32 s11, s10, 31
	s_lshl_b64 s[12:13], s[10:11], 20
	v_readlane_b32 s14, v254, 57
	v_readlane_b32 s15, v254, 58
	s_add_u32 s12, s14, s12
	s_addc_u32 s13, s15, s13
	s_and_b64 s[14:15], s[38:39], exec
	s_cselect_b32 s11, s13, s17
	s_cselect_b32 s30, s12, s16
	s_ashr_i32 s9, s8, 31
	s_lshl_b64 s[14:15], s[8:9], 20
	s_add_u32 s14, s54, s14
	s_addc_u32 s15, s55, s15
	s_and_b64 s[20:21], s[38:39], exec
	s_cselect_b32 s9, s15, s19
	s_cselect_b32 s31, s14, s18
	s_add_u32 s16, s16, 0x80080
	s_addc_u32 s17, s17, 0
	s_add_u32 s34, s18, 0x100
	v_mov_b32_e32 v0, 0
	s_addc_u32 s35, s19, 0
	s_mov_b32 s40, -2
	v_mov_b32_e32 v1, v0
	v_mov_b32_e32 v2, v0
	v_mov_b32_e32 v3, v0
	v_mov_b32_e32 v4, v0
	v_mov_b32_e32 v5, v0
	v_mov_b32_e32 v6, v0
	v_mov_b32_e32 v7, v0
	v_mov_b32_e32 v8, v0
	v_mov_b32_e32 v9, v0
	v_mov_b32_e32 v10, v0
	v_mov_b32_e32 v11, v0
	v_mov_b32_e32 v16, v0
	v_mov_b32_e32 v17, v0
	v_mov_b32_e32 v18, v0
	v_mov_b32_e32 v19, v0
	v_mov_b32_e32 v24, v0
	v_mov_b32_e32 v25, v0
	v_mov_b32_e32 v26, v0
	v_mov_b32_e32 v27, v0
	v_mov_b32_e32 v32, v0
	v_mov_b32_e32 v33, v0
	v_mov_b32_e32 v34, v0
	v_mov_b32_e32 v35, v0
	v_mov_b32_e32 v40, v0
	v_mov_b32_e32 v41, v0
	v_mov_b32_e32 v42, v0
	v_mov_b32_e32 v43, v0
	v_mov_b32_e32 v48, v0
	v_mov_b32_e32 v49, v0
	v_mov_b32_e32 v50, v0
	v_mov_b32_e32 v51, v0
	v_mov_b32_e32 v12, v0
	v_mov_b32_e32 v13, v0
	v_mov_b32_e32 v14, v0
	v_mov_b32_e32 v15, v0
	v_mov_b32_e32 v20, v0
	v_mov_b32_e32 v21, v0
	v_mov_b32_e32 v22, v0
	v_mov_b32_e32 v23, v0
	v_mov_b32_e32 v28, v0
	v_mov_b32_e32 v29, v0
	v_mov_b32_e32 v30, v0
	v_mov_b32_e32 v31, v0
	v_mov_b32_e32 v36, v0
	v_mov_b32_e32 v37, v0
	v_mov_b32_e32 v38, v0
	v_mov_b32_e32 v39, v0
	v_mov_b32_e32 v44, v0
	v_mov_b32_e32 v45, v0
	v_mov_b32_e32 v46, v0
	v_mov_b32_e32 v47, v0
	v_mov_b32_e32 v52, v0
	v_mov_b32_e32 v53, v0
	v_mov_b32_e32 v54, v0
	v_mov_b32_e32 v55, v0
	v_mov_b32_e32 v56, v0
	v_mov_b32_e32 v57, v0
	v_mov_b32_e32 v58, v0
	v_mov_b32_e32 v59, v0
	v_mov_b32_e32 v60, v0
	v_mov_b32_e32 v61, v0
	v_mov_b32_e32 v62, v0
	v_mov_b32_e32 v63, v0
	v_mov_b32_e32 v66, v0
	v_mov_b32_e32 v67, v0
	v_mov_b32_e32 v68, v0
	v_mov_b32_e32 v69, v0
	v_mov_b32_e32 v70, v0
	v_mov_b32_e32 v71, v0
	v_mov_b32_e32 v72, v0
	v_mov_b32_e32 v73, v0
	v_mov_b32_e32 v74, v0
	v_mov_b32_e32 v75, v0
	v_mov_b32_e32 v76, v0
	v_mov_b32_e32 v77, v0
	v_mov_b32_e32 v82, v0
	v_mov_b32_e32 v83, v0
	v_mov_b32_e32 v84, v0
	v_mov_b32_e32 v85, v0
	v_mov_b32_e32 v90, v0
	v_mov_b32_e32 v91, v0
	v_mov_b32_e32 v92, v0
	v_mov_b32_e32 v93, v0
	v_mov_b32_e32 v98, v0
	v_mov_b32_e32 v99, v0
	v_mov_b32_e32 v100, v0
	v_mov_b32_e32 v101, v0
	v_mov_b32_e32 v106, v0
	v_mov_b32_e32 v107, v0
	v_mov_b32_e32 v108, v0
	v_mov_b32_e32 v109, v0
	v_mov_b32_e32 v114, v0
	v_mov_b32_e32 v115, v0
	v_mov_b32_e32 v116, v0
	v_mov_b32_e32 v117, v0
	v_mov_b32_e32 v78, v0
	v_mov_b32_e32 v79, v0
	v_mov_b32_e32 v80, v0
	v_mov_b32_e32 v81, v0
	v_mov_b32_e32 v86, v0
	v_mov_b32_e32 v87, v0
	v_mov_b32_e32 v88, v0
	v_mov_b32_e32 v89, v0
	v_mov_b32_e32 v94, v0
	v_mov_b32_e32 v95, v0
	v_mov_b32_e32 v96, v0
	v_mov_b32_e32 v97, v0
	v_mov_b32_e32 v102, v0
	v_mov_b32_e32 v103, v0
	v_mov_b32_e32 v104, v0
	v_mov_b32_e32 v105, v0
	v_mov_b32_e32 v110, v0
	v_mov_b32_e32 v111, v0
	v_mov_b32_e32 v112, v0
	v_mov_b32_e32 v113, v0
	v_mov_b32_e32 v118, v0
	v_mov_b32_e32 v119, v0
	v_mov_b32_e32 v120, v0
	v_mov_b32_e32 v121, v0
	v_mov_b32_e32 v122, v0
	v_mov_b32_e32 v123, v0
	v_mov_b32_e32 v124, v0
	v_mov_b32_e32 v125, v0
	v_mov_b32_e32 v126, v0
	v_mov_b32_e32 v127, v0
	v_mov_b32_e32 v128, v0
	v_mov_b32_e32 v129, v0
	v_readfirstlane_b32 s98, v186
	s_cmpk_lt_u32 s98, 0x100
	s_cbranch_scc1 .Lgp_skip3
	s_setprio 1
.Lgp_skip3:
.LBB0_397:
	s_add_u32 s18, s16, 0xfff80080
	s_addc_u32 s19, s17, -1
	s_add_i32 s41, 0, 0x10000
	s_cmp_eq_u32 s40, 28
	s_cselect_b32 s21, s11, s19
	s_cselect_b32 s20, s30, s18
	v_add_u32_e32 v142, s41, v145
	s_cselect_b32 s19, s9, s35
	s_cselect_b32 s18, s31, s34
	s_add_i32 s44, 0, 0x14000
	ds_read_b128 v[154:157], v142
	ds_read_b128 v[158:161], v142 offset:1024
	ds_read_b128 v[174:177], v142 offset:2048
	ds_read_b128 v[178:181], v142 offset:3072
	v_add_u32_e32 v142, s44, v145
	ds_read_b128 v[182:185], v142
	ds_read_b128 v[200:203], v142 offset:1024
	ds_read_b128 v[204:207], v142 offset:2048
	ds_read_b128 v[208:211], v142 offset:3072
	v_lshl_add_u64 v[142:143], s[16:17], 0, v[138:139]
	s_add_i32 m0, s3, 0xc000
	ds_read_b128 v[212:215], v153
	ds_read_b128 v[216:219], v153 offset:1024
	ds_read_b128 v[220:223], v153 offset:2048
	ds_read_b128 v[224:227], v153 offset:3072
	ds_read_b128 v[228:231], v153 offset:4096
	ds_read_b128 v[232:235], v153 offset:5120
	ds_read_b128 v[236:239], v153 offset:6144
	ds_read_b128 v[240:243], v153 offset:7168
	global_load_lds_dwordx4 v[142:143], off
	v_lshl_add_u64 v[142:143], s[16:17], 0, v[140:141]
	s_add_i32 m0, s3, 0xe000
	s_nop 0
	global_load_lds_dwordx4 v[142:143], off
	s_waitcnt vmcnt(8)
	s_waitcnt lgkmcnt(0)
	s_barrier
	s_waitcnt lgkmcnt(0)
	v_mfma_f32_16x16x32_bf16 v[126:129], v[154:157], v[212:215], v[126:129]
	v_mfma_f32_16x16x32_bf16 v[122:125], v[174:177], v[212:215], v[122:125]
	v_mfma_f32_16x16x32_bf16 v[118:121], v[154:157], v[220:223], v[118:121]
	v_mfma_f32_16x16x32_bf16 v[110:113], v[174:177], v[220:223], v[110:113]
	v_mfma_f32_16x16x32_bf16 v[102:105], v[154:157], v[228:231], v[102:105]
	v_mfma_f32_16x16x32_bf16 v[94:97], v[174:177], v[228:231], v[94:97]
	v_mfma_f32_16x16x32_bf16 v[86:89], v[154:157], v[236:239], v[86:89]
	v_mfma_f32_16x16x32_bf16 v[78:81], v[174:177], v[236:239], v[78:81]
	v_mfma_f32_16x16x32_bf16 v[126:129], v[158:161], v[216:219], v[126:129]
	v_mfma_f32_16x16x32_bf16 v[122:125], v[178:181], v[216:219], v[122:125]
	v_mfma_f32_16x16x32_bf16 v[118:121], v[158:161], v[224:227], v[118:121]
	v_mfma_f32_16x16x32_bf16 v[110:113], v[178:181], v[224:227], v[110:113]
	v_mfma_f32_16x16x32_bf16 v[102:105], v[158:161], v[232:235], v[102:105]
	v_mfma_f32_16x16x32_bf16 v[94:97], v[178:181], v[232:235], v[94:97]
	v_mfma_f32_16x16x32_bf16 v[86:89], v[158:161], v[240:243], v[86:89]
	v_mfma_f32_16x16x32_bf16 v[78:81], v[178:181], v[240:243], v[78:81]
	v_mfma_f32_16x16x32_bf16 v[114:117], v[182:185], v[212:215], v[114:117]
	v_mfma_f32_16x16x32_bf16 v[106:109], v[204:207], v[212:215], v[106:109]
	v_mfma_f32_16x16x32_bf16 v[98:101], v[182:185], v[220:223], v[98:101]
	v_mfma_f32_16x16x32_bf16 v[90:93], v[204:207], v[220:223], v[90:93]
	v_mfma_f32_16x16x32_bf16 v[82:85], v[182:185], v[228:231], v[82:85]
	v_mfma_f32_16x16x32_bf16 v[74:77], v[204:207], v[228:231], v[74:77]
	v_mfma_f32_16x16x32_bf16 v[70:73], v[182:185], v[236:239], v[70:73]
	v_mfma_f32_16x16x32_bf16 v[66:69], v[204:207], v[236:239], v[66:69]
	v_mfma_f32_16x16x32_bf16 v[114:117], v[200:203], v[216:219], v[114:117]
	v_mfma_f32_16x16x32_bf16 v[106:109], v[208:211], v[216:219], v[106:109]
	v_mfma_f32_16x16x32_bf16 v[98:101], v[200:203], v[224:227], v[98:101]
	v_mfma_f32_16x16x32_bf16 v[90:93], v[208:211], v[224:227], v[90:93]
	v_mfma_f32_16x16x32_bf16 v[82:85], v[200:203], v[232:235], v[82:85]
	v_mfma_f32_16x16x32_bf16 v[74:77], v[208:211], v[232:235], v[74:77]
	v_mfma_f32_16x16x32_bf16 v[70:73], v[200:203], v[240:243], v[70:73]
	v_mfma_f32_16x16x32_bf16 v[66:69], v[208:211], v[240:243], v[66:69]
	s_barrier
	s_add_i32 s41, s41, s2
	v_lshl_add_u64 v[142:143], s[18:19], 0, v[134:135]
	s_mov_b32 m0, s41
	ds_read_b128 v[212:215], v153 offset:16384
	ds_read_b128 v[216:219], v153 offset:17408
	ds_read_b128 v[220:223], v153 offset:18432
	ds_read_b128 v[224:227], v153 offset:19456
	ds_read_b128 v[228:231], v153 offset:20480
	ds_read_b128 v[232:235], v153 offset:21504
	ds_read_b128 v[236:239], v153 offset:22528
	ds_read_b128 v[240:243], v153 offset:23552
	global_load_lds_dwordx4 v[142:143], off
	s_add_i32 m0, s41, 0x2000
	s_add_u32 s42, s18, 0x80000
	v_lshl_add_u64 v[244:245], s[18:19], 0, v[130:131]
	s_addc_u32 s43, s19, 0
	s_add_i32 s41, s44, s2
	global_load_lds_dwordx4 v[244:245], off
	v_lshl_add_u64 v[246:247], s[42:43], 0, v[134:135]
	s_mov_b32 m0, s41
	v_lshl_add_u64 v[248:249], s[20:21], 0, v[132:133]
	global_load_lds_dwordx4 v[246:247], off
	v_lshl_add_u64 v[246:247], s[42:43], 0, v[130:131]
	s_add_i32 m0, s41, 0x2000
	s_nop 0
	global_load_lds_dwordx4 v[246:247], off
	v_lshl_add_u64 v[246:247], s[20:21], 0, v[136:137]
	s_mov_b32 m0, s3
	s_nop 0
	global_load_lds_dwordx4 v[246:247], off
	s_mov_b32 m0, s22
	s_nop 0
	global_load_lds_dwordx4 v[248:249], off
	s_waitcnt vmcnt(8)
	s_waitcnt lgkmcnt(0)
	s_barrier
	s_waitcnt lgkmcnt(0)
	v_mfma_f32_16x16x32_bf16 v[60:63], v[154:157], v[212:215], v[60:63]
	v_mfma_f32_16x16x32_bf16 v[56:59], v[174:177], v[212:215], v[56:59]
	v_mfma_f32_16x16x32_bf16 v[52:55], v[154:157], v[220:223], v[52:55]
	v_mfma_f32_16x16x32_bf16 v[44:47], v[174:177], v[220:223], v[44:47]
	v_mfma_f32_16x16x32_bf16 v[36:39], v[154:157], v[228:231], v[36:39]
	v_mfma_f32_16x16x32_bf16 v[28:31], v[174:177], v[228:231], v[28:31]
	v_mfma_f32_16x16x32_bf16 v[20:23], v[154:157], v[236:239], v[20:23]
	v_mfma_f32_16x16x32_bf16 v[12:15], v[174:177], v[236:239], v[12:15]
	v_mfma_f32_16x16x32_bf16 v[60:63], v[158:161], v[216:219], v[60:63]
	v_mfma_f32_16x16x32_bf16 v[56:59], v[178:181], v[216:219], v[56:59]
	v_mfma_f32_16x16x32_bf16 v[52:55], v[158:161], v[224:227], v[52:55]
	v_mfma_f32_16x16x32_bf16 v[44:47], v[178:181], v[224:227], v[44:47]
	v_mfma_f32_16x16x32_bf16 v[36:39], v[158:161], v[232:235], v[36:39]
	v_mfma_f32_16x16x32_bf16 v[28:31], v[178:181], v[232:235], v[28:31]
	v_mfma_f32_16x16x32_bf16 v[20:23], v[158:161], v[240:243], v[20:23]
	v_mfma_f32_16x16x32_bf16 v[12:15], v[178:181], v[240:243], v[12:15]
	v_mfma_f32_16x16x32_bf16 v[48:51], v[182:185], v[212:215], v[48:51]
	v_mfma_f32_16x16x32_bf16 v[40:43], v[204:207], v[212:215], v[40:43]
	v_mfma_f32_16x16x32_bf16 v[32:35], v[182:185], v[220:223], v[32:35]
	v_mfma_f32_16x16x32_bf16 v[24:27], v[204:207], v[220:223], v[24:27]
	v_mfma_f32_16x16x32_bf16 v[16:19], v[182:185], v[228:231], v[16:19]
	v_mfma_f32_16x16x32_bf16 v[8:11], v[204:207], v[228:231], v[8:11]
	v_mfma_f32_16x16x32_bf16 v[4:7], v[182:185], v[236:239], v[4:7]
	v_mfma_f32_16x16x32_bf16 v[0:3], v[204:207], v[236:239], v[0:3]
	v_mfma_f32_16x16x32_bf16 v[48:51], v[200:203], v[216:219], v[48:51]
	v_mfma_f32_16x16x32_bf16 v[40:43], v[208:211], v[216:219], v[40:43]
	v_mfma_f32_16x16x32_bf16 v[32:35], v[200:203], v[224:227], v[32:35]
	v_mfma_f32_16x16x32_bf16 v[24:27], v[208:211], v[224:227], v[24:27]
	v_mfma_f32_16x16x32_bf16 v[16:19], v[200:203], v[232:235], v[16:19]
	v_mfma_f32_16x16x32_bf16 v[8:11], v[208:211], v[232:235], v[8:11]
	v_mfma_f32_16x16x32_bf16 v[4:7], v[200:203], v[240:243], v[4:7]
	v_mfma_f32_16x16x32_bf16 v[0:3], v[208:211], v[240:243], v[0:3]
	s_barrier
	s_add_i32 s41, 0, 0x18000
	s_add_i32 s42, 0, 0x1c000
	v_add_u32_e32 v178, s41, v145
	v_add_u32_e32 v199, s42, v145
	ds_read_b128 v[154:157], v178
	ds_read_b128 v[158:161], v178 offset:1024
	ds_read_b128 v[174:177], v178 offset:2048
	ds_read_b128 v[178:181], v178 offset:3072
	ds_read_b128 v[182:185], v199
	ds_read_b128 v[200:203], v199 offset:1024
	ds_read_b128 v[204:207], v199 offset:2048
	ds_read_b128 v[208:211], v199 offset:3072
	s_add_u32 s20, s20, 0x80000
	s_addc_u32 s21, s21, 0
	s_mov_b32 m0, s23
	v_lshl_add_u64 v[250:251], s[20:21], 0, v[136:137]
	ds_read_b128 v[212:215], v153 offset:32768
	ds_read_b128 v[216:219], v153 offset:33792
	ds_read_b128 v[220:223], v153 offset:34816
	ds_read_b128 v[224:227], v153 offset:35840
	ds_read_b128 v[228:231], v153 offset:36864
	ds_read_b128 v[232:235], v153 offset:37888
	ds_read_b128 v[236:239], v153 offset:38912
	ds_read_b128 v[240:243], v153 offset:39936
	global_load_lds_dwordx4 v[250:251], off
	v_lshl_add_u64 v[250:251], s[20:21], 0, v[132:133]
	s_mov_b32 m0, s24
	s_nop 0
	global_load_lds_dwordx4 v[250:251], off
	s_waitcnt vmcnt(8)
	s_waitcnt lgkmcnt(0)
	s_barrier
	s_waitcnt lgkmcnt(0)
	v_mfma_f32_16x16x32_bf16 v[126:129], v[154:157], v[212:215], v[126:129]
	v_mfma_f32_16x16x32_bf16 v[122:125], v[174:177], v[212:215], v[122:125]
	v_mfma_f32_16x16x32_bf16 v[118:121], v[154:157], v[220:223], v[118:121]
	v_mfma_f32_16x16x32_bf16 v[110:113], v[174:177], v[220:223], v[110:113]
	v_mfma_f32_16x16x32_bf16 v[102:105], v[154:157], v[228:231], v[102:105]
	v_mfma_f32_16x16x32_bf16 v[94:97], v[174:177], v[228:231], v[94:97]
	v_mfma_f32_16x16x32_bf16 v[86:89], v[154:157], v[236:239], v[86:89]
	v_mfma_f32_16x16x32_bf16 v[78:81], v[174:177], v[236:239], v[78:81]
	v_mfma_f32_16x16x32_bf16 v[126:129], v[158:161], v[216:219], v[126:129]
	v_mfma_f32_16x16x32_bf16 v[122:125], v[178:181], v[216:219], v[122:125]
	v_mfma_f32_16x16x32_bf16 v[118:121], v[158:161], v[224:227], v[118:121]
	v_mfma_f32_16x16x32_bf16 v[110:113], v[178:181], v[224:227], v[110:113]
	v_mfma_f32_16x16x32_bf16 v[102:105], v[158:161], v[232:235], v[102:105]
	v_mfma_f32_16x16x32_bf16 v[94:97], v[178:181], v[232:235], v[94:97]
	v_mfma_f32_16x16x32_bf16 v[86:89], v[158:161], v[240:243], v[86:89]
	v_mfma_f32_16x16x32_bf16 v[78:81], v[178:181], v[240:243], v[78:81]
	v_mfma_f32_16x16x32_bf16 v[114:117], v[182:185], v[212:215], v[114:117]
	v_mfma_f32_16x16x32_bf16 v[106:109], v[204:207], v[212:215], v[106:109]
	v_mfma_f32_16x16x32_bf16 v[98:101], v[182:185], v[220:223], v[98:101]
	v_mfma_f32_16x16x32_bf16 v[90:93], v[204:207], v[220:223], v[90:93]
	v_mfma_f32_16x16x32_bf16 v[82:85], v[182:185], v[228:231], v[82:85]
	v_mfma_f32_16x16x32_bf16 v[74:77], v[204:207], v[228:231], v[74:77]
	v_mfma_f32_16x16x32_bf16 v[70:73], v[182:185], v[236:239], v[70:73]
	v_mfma_f32_16x16x32_bf16 v[66:69], v[204:207], v[236:239], v[66:69]
	v_mfma_f32_16x16x32_bf16 v[114:117], v[200:203], v[216:219], v[114:117]
	v_mfma_f32_16x16x32_bf16 v[106:109], v[208:211], v[216:219], v[106:109]
	v_mfma_f32_16x16x32_bf16 v[98:101], v[200:203], v[224:227], v[98:101]
	v_mfma_f32_16x16x32_bf16 v[90:93], v[208:211], v[224:227], v[90:93]
	v_mfma_f32_16x16x32_bf16 v[82:85], v[200:203], v[232:235], v[82:85]
	v_mfma_f32_16x16x32_bf16 v[74:77], v[208:211], v[232:235], v[74:77]
	v_mfma_f32_16x16x32_bf16 v[70:73], v[200:203], v[240:243], v[70:73]
	v_mfma_f32_16x16x32_bf16 v[66:69], v[208:211], v[240:243], v[66:69]
	s_barrier
	s_add_i32 s20, s41, s2
	v_lshl_add_u64 v[142:143], v[142:143], 0, s[94:95]
	s_mov_b32 m0, s20
	ds_read_b128 v[212:215], v153 offset:49152
	ds_read_b128 v[216:219], v153 offset:50176
	ds_read_b128 v[220:223], v153 offset:51200
	ds_read_b128 v[224:227], v153 offset:52224
	ds_read_b128 v[228:231], v153 offset:53248
	ds_read_b128 v[232:235], v153 offset:54272
	ds_read_b128 v[236:239], v153 offset:55296
	ds_read_b128 v[240:243], v153 offset:56320
	global_load_lds_dwordx4 v[142:143], off
	s_add_i32 m0, s20, 0x2000
	s_add_u32 s18, s18, 0x80080
	v_lshl_add_u64 v[142:143], v[244:245], 0, s[94:95]
	s_addc_u32 s19, s19, 0
	s_add_i32 s20, s42, s2
	global_load_lds_dwordx4 v[142:143], off
	v_lshl_add_u64 v[142:143], s[18:19], 0, v[134:135]
	s_mov_b32 m0, s20
	s_nop 0
	global_load_lds_dwordx4 v[142:143], off
	v_lshl_add_u64 v[142:143], s[18:19], 0, v[130:131]
	s_add_i32 m0, s20, 0x2000
	s_nop 0
	global_load_lds_dwordx4 v[142:143], off
	v_lshl_add_u64 v[142:143], v[246:247], 0, s[94:95]
	s_mov_b32 m0, s25
	s_nop 0
	global_load_lds_dwordx4 v[142:143], off
	v_lshl_add_u64 v[142:143], v[248:249], 0, s[94:95]
	s_mov_b32 m0, s26
	s_nop 0
	global_load_lds_dwordx4 v[142:143], off
	s_waitcnt vmcnt(8)
	s_waitcnt lgkmcnt(0)
	s_barrier
	s_waitcnt lgkmcnt(0)
	v_mfma_f32_16x16x32_bf16 v[60:63], v[154:157], v[212:215], v[60:63]
	v_mfma_f32_16x16x32_bf16 v[56:59], v[174:177], v[212:215], v[56:59]
	v_mfma_f32_16x16x32_bf16 v[52:55], v[154:157], v[220:223], v[52:55]
	v_mfma_f32_16x16x32_bf16 v[44:47], v[174:177], v[220:223], v[44:47]
	v_mfma_f32_16x16x32_bf16 v[36:39], v[154:157], v[228:231], v[36:39]
	v_mfma_f32_16x16x32_bf16 v[28:31], v[174:177], v[228:231], v[28:31]
	v_mfma_f32_16x16x32_bf16 v[20:23], v[154:157], v[236:239], v[20:23]
	v_mfma_f32_16x16x32_bf16 v[12:15], v[174:177], v[236:239], v[12:15]
	v_mfma_f32_16x16x32_bf16 v[60:63], v[158:161], v[216:219], v[60:63]
	v_mfma_f32_16x16x32_bf16 v[56:59], v[178:181], v[216:219], v[56:59]
	v_mfma_f32_16x16x32_bf16 v[52:55], v[158:161], v[224:227], v[52:55]
	v_mfma_f32_16x16x32_bf16 v[44:47], v[178:181], v[224:227], v[44:47]
	v_mfma_f32_16x16x32_bf16 v[36:39], v[158:161], v[232:235], v[36:39]
	v_mfma_f32_16x16x32_bf16 v[28:31], v[178:181], v[232:235], v[28:31]
	v_mfma_f32_16x16x32_bf16 v[20:23], v[158:161], v[240:243], v[20:23]
	v_mfma_f32_16x16x32_bf16 v[12:15], v[178:181], v[240:243], v[12:15]
	v_mfma_f32_16x16x32_bf16 v[48:51], v[182:185], v[212:215], v[48:51]
	v_mfma_f32_16x16x32_bf16 v[40:43], v[204:207], v[212:215], v[40:43]
	v_mfma_f32_16x16x32_bf16 v[32:35], v[182:185], v[220:223], v[32:35]
	v_mfma_f32_16x16x32_bf16 v[24:27], v[204:207], v[220:223], v[24:27]
	v_mfma_f32_16x16x32_bf16 v[16:19], v[182:185], v[228:231], v[16:19]
	v_mfma_f32_16x16x32_bf16 v[8:11], v[204:207], v[228:231], v[8:11]
	v_mfma_f32_16x16x32_bf16 v[4:7], v[182:185], v[236:239], v[4:7]
	v_mfma_f32_16x16x32_bf16 v[0:3], v[204:207], v[236:239], v[0:3]
	v_mfma_f32_16x16x32_bf16 v[48:51], v[200:203], v[216:219], v[48:51]
	v_mfma_f32_16x16x32_bf16 v[40:43], v[208:211], v[216:219], v[40:43]
	v_mfma_f32_16x16x32_bf16 v[32:35], v[200:203], v[224:227], v[32:35]
	v_mfma_f32_16x16x32_bf16 v[24:27], v[208:211], v[224:227], v[24:27]
	v_mfma_f32_16x16x32_bf16 v[16:19], v[200:203], v[232:235], v[16:19]
	v_mfma_f32_16x16x32_bf16 v[8:11], v[208:211], v[232:235], v[8:11]
	v_mfma_f32_16x16x32_bf16 v[4:7], v[200:203], v[240:243], v[4:7]
	v_mfma_f32_16x16x32_bf16 v[0:3], v[208:211], v[240:243], v[0:3]
	s_barrier
	s_add_i32 s40, s40, 2
	s_add_u32 s16, s16, 0x100
	s_addc_u32 s17, s17, 0
	s_add_u32 s34, s34, 0x100
	s_addc_u32 s35, s35, 0
	s_cmp_gt_u32 s40, 29
	s_cbranch_scc0 .LBB0_397
	s_setprio 0
	s_and_b64 vcc, exec, s[6:7]
	s_cbranch_vccz .LBB0_400
	s_barrier

.LBB0_556:
	s_add_u32 s34, s12, 0x100
	v_mov_b32_e32 v0, 0
	s_addc_u32 s35, s13, 0
	s_mov_b32 s36, -2
	v_mov_b32_e32 v1, v0
	v_mov_b32_e32 v2, v0
	v_mov_b32_e32 v3, v0
	v_mov_b32_e32 v4, v0
	v_mov_b32_e32 v5, v0
	v_mov_b32_e32 v6, v0
	v_mov_b32_e32 v7, v0
	v_mov_b32_e32 v8, v0
	v_mov_b32_e32 v9, v0
	v_mov_b32_e32 v10, v0
	v_mov_b32_e32 v11, v0
	v_mov_b32_e32 v16, v0
	v_mov_b32_e32 v17, v0
	v_mov_b32_e32 v18, v0
	v_mov_b32_e32 v19, v0
	v_mov_b32_e32 v32, v0
	v_mov_b32_e32 v33, v0
	v_mov_b32_e32 v34, v0
	v_mov_b32_e32 v35, v0
	v_mov_b32_e32 v36, v0
	v_mov_b32_e32 v37, v0
	v_mov_b32_e32 v38, v0
	v_mov_b32_e32 v39, v0
	v_mov_b32_e32 v48, v0
	v_mov_b32_e32 v49, v0
	v_mov_b32_e32 v50, v0
	v_mov_b32_e32 v51, v0
	v_mov_b32_e32 v52, v0
	v_mov_b32_e32 v53, v0
	v_mov_b32_e32 v54, v0
	v_mov_b32_e32 v55, v0
	v_mov_b32_e32 v12, v0
	v_mov_b32_e32 v13, v0
	v_mov_b32_e32 v14, v0
	v_mov_b32_e32 v15, v0
	v_mov_b32_e32 v20, v0
	v_mov_b32_e32 v21, v0
	v_mov_b32_e32 v22, v0
	v_mov_b32_e32 v23, v0
	v_mov_b32_e32 v24, v0
	v_mov_b32_e32 v25, v0
	v_mov_b32_e32 v26, v0
	v_mov_b32_e32 v27, v0
	v_mov_b32_e32 v28, v0
	v_mov_b32_e32 v29, v0
	v_mov_b32_e32 v30, v0
	v_mov_b32_e32 v31, v0
	v_mov_b32_e32 v40, v0
	v_mov_b32_e32 v41, v0
	v_mov_b32_e32 v42, v0
	v_mov_b32_e32 v43, v0
	v_mov_b32_e32 v44, v0
	v_mov_b32_e32 v45, v0
	v_mov_b32_e32 v46, v0
	v_mov_b32_e32 v47, v0
	v_mov_b32_e32 v56, v0
	v_mov_b32_e32 v57, v0
	v_mov_b32_e32 v58, v0
	v_mov_b32_e32 v59, v0
	v_mov_b32_e32 v60, v0
	v_mov_b32_e32 v61, v0
	v_mov_b32_e32 v62, v0
	v_mov_b32_e32 v63, v0
	v_mov_b32_e32 v66, v0
	v_mov_b32_e32 v67, v0
	v_mov_b32_e32 v68, v0
	v_mov_b32_e32 v69, v0
	v_mov_b32_e32 v70, v0
	v_mov_b32_e32 v71, v0
	v_mov_b32_e32 v72, v0
	v_mov_b32_e32 v73, v0
	v_mov_b32_e32 v82, v0
	v_mov_b32_e32 v83, v0
	v_mov_b32_e32 v84, v0
	v_mov_b32_e32 v85, v0
	v_mov_b32_e32 v86, v0
	v_mov_b32_e32 v87, v0
	v_mov_b32_e32 v88, v0
	v_mov_b32_e32 v89, v0
	v_mov_b32_e32 v98, v0
	v_mov_b32_e32 v99, v0
	v_mov_b32_e32 v100, v0
	v_mov_b32_e32 v101, v0
	v_mov_b32_e32 v102, v0
	v_mov_b32_e32 v103, v0
	v_mov_b32_e32 v104, v0
	v_mov_b32_e32 v105, v0
	v_mov_b32_e32 v114, v0
	v_mov_b32_e32 v115, v0
	v_mov_b32_e32 v116, v0
	v_mov_b32_e32 v117, v0
	v_mov_b32_e32 v118, v0
	v_mov_b32_e32 v119, v0
	v_mov_b32_e32 v120, v0
	v_mov_b32_e32 v121, v0
	v_mov_b32_e32 v74, v0
	v_mov_b32_e32 v75, v0
	v_mov_b32_e32 v76, v0
	v_mov_b32_e32 v77, v0
	v_mov_b32_e32 v78, v0
	v_mov_b32_e32 v79, v0
	v_mov_b32_e32 v80, v0
	v_mov_b32_e32 v81, v0
	v_mov_b32_e32 v90, v0
	v_mov_b32_e32 v91, v0
	v_mov_b32_e32 v92, v0
	v_mov_b32_e32 v93, v0
	v_mov_b32_e32 v94, v0
	v_mov_b32_e32 v95, v0
	v_mov_b32_e32 v96, v0
	v_mov_b32_e32 v97, v0
	v_mov_b32_e32 v106, v0
	v_mov_b32_e32 v107, v0
	v_mov_b32_e32 v108, v0
	v_mov_b32_e32 v109, v0
	v_mov_b32_e32 v110, v0
	v_mov_b32_e32 v111, v0
	v_mov_b32_e32 v112, v0
	v_mov_b32_e32 v113, v0
	v_mov_b32_e32 v122, v0
	v_mov_b32_e32 v123, v0
	v_mov_b32_e32 v124, v0
	v_mov_b32_e32 v125, v0
	v_mov_b32_e32 v126, v0
	v_mov_b32_e32 v127, v0
	v_mov_b32_e32 v128, v0
	v_mov_b32_e32 v129, v0
	v_readfirstlane_b32 s98, v186
	s_cmpk_lt_u32 s98, 0x100
	s_cbranch_scc1 .Lgp_skip4
	s_setprio 1
.Lgp_skip4:
.LBB0_557:
	s_add_u32 s12, s10, 0x100
	s_addc_u32 s13, s11, 0
	s_add_i32 s40, 0, 0x10000
	s_cmpk_eq_i32 s36, 0x54
	s_cselect_b32 s17, s1, s13
	s_cselect_b32 s16, s0, s12
	v_add_u32_e32 v142, s40, v145
	s_cselect_b32 s15, s9, s35
	s_cselect_b32 s14, s8, s34
	s_add_i32 s41, 0, 0x14000
	ds_read_b128 v[148:151], v142
	ds_read_b128 v[152:155], v142 offset:1024
	ds_read_b128 v[156:159], v142 offset:2048
	ds_read_b128 v[174:177], v142 offset:3072
	v_add_u32_e32 v142, s41, v145
	ds_read_b128 v[178:181], v142
	ds_read_b128 v[182:185], v142 offset:1024
	ds_read_b128 v[200:203], v142 offset:2048
	ds_read_b128 v[204:207], v142 offset:3072
	v_lshl_add_u64 v[142:143], s[10:11], 0, v[138:139]
	s_add_i32 m0, s23, 0xc000
	ds_read_b128 v[208:211], v146
	ds_read_b128 v[212:215], v146 offset:1024
	ds_read_b128 v[216:219], v146 offset:2048
	ds_read_b128 v[220:223], v146 offset:3072
	ds_read_b128 v[224:227], v146 offset:4096
	ds_read_b128 v[228:231], v146 offset:5120
	ds_read_b128 v[232:235], v146 offset:6144
	ds_read_b128 v[236:239], v146 offset:7168
	global_load_lds_dwordx4 v[142:143], off
	v_lshl_add_u64 v[142:143], s[10:11], 0, v[140:141]
	s_add_i32 m0, s23, 0xe000
	s_nop 0
	global_load_lds_dwordx4 v[142:143], off
	s_waitcnt vmcnt(8)
	s_waitcnt lgkmcnt(0)
	s_barrier
	s_waitcnt lgkmcnt(0)
	v_mfma_f32_16x16x32_bf16 v[126:129], v[148:151], v[208:211], v[126:129]
	v_mfma_f32_16x16x32_bf16 v[122:125], v[156:159], v[208:211], v[122:125]
	v_mfma_f32_16x16x32_bf16 v[110:113], v[148:151], v[216:219], v[110:113]
	v_mfma_f32_16x16x32_bf16 v[106:109], v[156:159], v[216:219], v[106:109]
	v_mfma_f32_16x16x32_bf16 v[94:97], v[148:151], v[224:227], v[94:97]
	v_mfma_f32_16x16x32_bf16 v[90:93], v[156:159], v[224:227], v[90:93]
	v_mfma_f32_16x16x32_bf16 v[78:81], v[148:151], v[232:235], v[78:81]
	v_mfma_f32_16x16x32_bf16 v[74:77], v[156:159], v[232:235], v[74:77]
	v_mfma_f32_16x16x32_bf16 v[126:129], v[152:155], v[212:215], v[126:129]
	v_mfma_f32_16x16x32_bf16 v[122:125], v[174:177], v[212:215], v[122:125]
	v_mfma_f32_16x16x32_bf16 v[110:113], v[152:155], v[220:223], v[110:113]
	v_mfma_f32_16x16x32_bf16 v[106:109], v[174:177], v[220:223], v[106:109]
	v_mfma_f32_16x16x32_bf16 v[94:97], v[152:155], v[228:231], v[94:97]
	v_mfma_f32_16x16x32_bf16 v[90:93], v[174:177], v[228:231], v[90:93]
	v_mfma_f32_16x16x32_bf16 v[78:81], v[152:155], v[236:239], v[78:81]
	v_mfma_f32_16x16x32_bf16 v[74:77], v[174:177], v[236:239], v[74:77]
	v_mfma_f32_16x16x32_bf16 v[118:121], v[178:181], v[208:211], v[118:121]
	v_mfma_f32_16x16x32_bf16 v[114:117], v[200:203], v[208:211], v[114:117]
	v_mfma_f32_16x16x32_bf16 v[102:105], v[178:181], v[216:219], v[102:105]
	v_mfma_f32_16x16x32_bf16 v[98:101], v[200:203], v[216:219], v[98:101]
	v_mfma_f32_16x16x32_bf16 v[86:89], v[178:181], v[224:227], v[86:89]
	v_mfma_f32_16x16x32_bf16 v[82:85], v[200:203], v[224:227], v[82:85]
	v_mfma_f32_16x16x32_bf16 v[70:73], v[178:181], v[232:235], v[70:73]
	v_mfma_f32_16x16x32_bf16 v[66:69], v[200:203], v[232:235], v[66:69]
	v_mfma_f32_16x16x32_bf16 v[118:121], v[182:185], v[212:215], v[118:121]
	v_mfma_f32_16x16x32_bf16 v[114:117], v[204:207], v[212:215], v[114:117]
	v_mfma_f32_16x16x32_bf16 v[102:105], v[182:185], v[220:223], v[102:105]
	v_mfma_f32_16x16x32_bf16 v[98:101], v[204:207], v[220:223], v[98:101]
	v_mfma_f32_16x16x32_bf16 v[86:89], v[182:185], v[228:231], v[86:89]
	v_mfma_f32_16x16x32_bf16 v[82:85], v[204:207], v[228:231], v[82:85]
	v_mfma_f32_16x16x32_bf16 v[70:73], v[182:185], v[236:239], v[70:73]
	v_mfma_f32_16x16x32_bf16 v[66:69], v[204:207], v[236:239], v[66:69]
	s_barrier
	s_add_i32 s10, s40, s22
	v_lshl_add_u64 v[142:143], s[14:15], 0, v[134:135]
	s_mov_b32 m0, s10
	ds_read_b128 v[208:211], v146 offset:16384
	ds_read_b128 v[212:215], v146 offset:17408
	ds_read_b128 v[216:219], v146 offset:18432
	ds_read_b128 v[220:223], v146 offset:19456
	ds_read_b128 v[224:227], v146 offset:20480
	ds_read_b128 v[228:231], v146 offset:21504
	ds_read_b128 v[232:235], v146 offset:22528
	ds_read_b128 v[236:239], v146 offset:23552
	global_load_lds_dwordx4 v[142:143], off
	s_add_i32 m0, s10, 0x2000
	s_add_u32 s10, s14, 0x160000
	v_lshl_add_u64 v[160:161], s[14:15], 0, v[130:131]
	s_addc_u32 s11, s15, 0
	s_add_i32 s40, s41, s22
	global_load_lds_dwordx4 v[160:161], off
	v_lshl_add_u64 v[240:241], s[10:11], 0, v[134:135]
	s_mov_b32 m0, s40
	v_lshl_add_u64 v[242:243], s[16:17], 0, v[132:133]
	global_load_lds_dwordx4 v[240:241], off
	v_lshl_add_u64 v[240:241], s[10:11], 0, v[130:131]
	s_add_i32 m0, s40, 0x2000
	s_nop 0
	global_load_lds_dwordx4 v[240:241], off
	v_lshl_add_u64 v[240:241], s[16:17], 0, v[136:137]
	s_mov_b32 m0, s23
	s_nop 0
	global_load_lds_dwordx4 v[240:241], off
	s_mov_b32 m0, s24
	s_nop 0
	global_load_lds_dwordx4 v[242:243], off
	s_waitcnt vmcnt(8)
	s_waitcnt lgkmcnt(0)
	s_barrier
	s_waitcnt lgkmcnt(0)
	v_mfma_f32_16x16x32_bf16 v[60:63], v[148:151], v[208:211], v[60:63]
	v_mfma_f32_16x16x32_bf16 v[56:59], v[156:159], v[208:211], v[56:59]
	v_mfma_f32_16x16x32_bf16 v[44:47], v[148:151], v[216:219], v[44:47]
	v_mfma_f32_16x16x32_bf16 v[40:43], v[156:159], v[216:219], v[40:43]
	v_mfma_f32_16x16x32_bf16 v[28:31], v[148:151], v[224:227], v[28:31]
	v_mfma_f32_16x16x32_bf16 v[24:27], v[156:159], v[224:227], v[24:27]
	v_mfma_f32_16x16x32_bf16 v[20:23], v[148:151], v[232:235], v[20:23]
	v_mfma_f32_16x16x32_bf16 v[12:15], v[156:159], v[232:235], v[12:15]
	v_mfma_f32_16x16x32_bf16 v[60:63], v[152:155], v[212:215], v[60:63]
	v_mfma_f32_16x16x32_bf16 v[56:59], v[174:177], v[212:215], v[56:59]
	v_mfma_f32_16x16x32_bf16 v[44:47], v[152:155], v[220:223], v[44:47]
	v_mfma_f32_16x16x32_bf16 v[40:43], v[174:177], v[220:223], v[40:43]
	v_mfma_f32_16x16x32_bf16 v[28:31], v[152:155], v[228:231], v[28:31]
	v_mfma_f32_16x16x32_bf16 v[24:27], v[174:177], v[228:231], v[24:27]
	v_mfma_f32_16x16x32_bf16 v[20:23], v[152:155], v[236:239], v[20:23]
	v_mfma_f32_16x16x32_bf16 v[12:15], v[174:177], v[236:239], v[12:15]
	v_mfma_f32_16x16x32_bf16 v[52:55], v[178:181], v[208:211], v[52:55]
	v_mfma_f32_16x16x32_bf16 v[48:51], v[200:203], v[208:211], v[48:51]
	v_mfma_f32_16x16x32_bf16 v[36:39], v[178:181], v[216:219], v[36:39]
	v_mfma_f32_16x16x32_bf16 v[32:35], v[200:203], v[216:219], v[32:35]
	v_mfma_f32_16x16x32_bf16 v[16:19], v[178:181], v[224:227], v[16:19]
	v_mfma_f32_16x16x32_bf16 v[8:11], v[200:203], v[224:227], v[8:11]
	v_mfma_f32_16x16x32_bf16 v[4:7], v[178:181], v[232:235], v[4:7]
	v_mfma_f32_16x16x32_bf16 v[0:3], v[200:203], v[232:235], v[0:3]
	v_mfma_f32_16x16x32_bf16 v[52:55], v[182:185], v[212:215], v[52:55]
	v_mfma_f32_16x16x32_bf16 v[48:51], v[204:207], v[212:215], v[48:51]
	v_mfma_f32_16x16x32_bf16 v[36:39], v[182:185], v[220:223], v[36:39]
	v_mfma_f32_16x16x32_bf16 v[32:35], v[204:207], v[220:223], v[32:35]
	v_mfma_f32_16x16x32_bf16 v[16:19], v[182:185], v[228:231], v[16:19]
	v_mfma_f32_16x16x32_bf16 v[8:11], v[204:207], v[228:231], v[8:11]
	v_mfma_f32_16x16x32_bf16 v[4:7], v[182:185], v[236:239], v[4:7]
	v_mfma_f32_16x16x32_bf16 v[0:3], v[204:207], v[236:239], v[0:3]
	s_barrier
	s_add_i32 s40, 0, 0x18000
	v_add_u32_e32 v147, s40, v145
	s_add_i32 s41, 0, 0x1c000
	ds_read_b128 v[148:151], v147
	ds_read_b128 v[152:155], v147 offset:1024
	ds_read_b128 v[156:159], v147 offset:2048
	ds_read_b128 v[174:177], v147 offset:3072
	v_add_u32_e32 v147, s41, v145
	ds_read_b128 v[178:181], v147
	ds_read_b128 v[182:185], v147 offset:1024
	ds_read_b128 v[200:203], v147 offset:2048
	ds_read_b128 v[204:207], v147 offset:3072
	s_add_u32 s10, s16, 0x160000
	s_addc_u32 s11, s17, 0
	s_mov_b32 m0, s25
	v_lshl_add_u64 v[244:245], s[10:11], 0, v[136:137]
	ds_read_b128 v[208:211], v146 offset:32768
	ds_read_b128 v[212:215], v146 offset:33792
	ds_read_b128 v[216:219], v146 offset:34816
	ds_read_b128 v[220:223], v146 offset:35840
	ds_read_b128 v[224:227], v146 offset:36864
	ds_read_b128 v[228:231], v146 offset:37888
	ds_read_b128 v[232:235], v146 offset:38912
	ds_read_b128 v[236:239], v146 offset:39936
	global_load_lds_dwordx4 v[244:245], off
	v_lshl_add_u64 v[244:245], s[10:11], 0, v[132:133]
	s_mov_b32 m0, s26
	s_nop 0
	global_load_lds_dwordx4 v[244:245], off
	s_waitcnt vmcnt(8)
	s_waitcnt lgkmcnt(0)
	s_barrier
	s_waitcnt lgkmcnt(0)
	v_mfma_f32_16x16x32_bf16 v[126:129], v[148:151], v[208:211], v[126:129]
	v_mfma_f32_16x16x32_bf16 v[122:125], v[156:159], v[208:211], v[122:125]
	v_mfma_f32_16x16x32_bf16 v[110:113], v[148:151], v[216:219], v[110:113]
	v_mfma_f32_16x16x32_bf16 v[106:109], v[156:159], v[216:219], v[106:109]
	v_mfma_f32_16x16x32_bf16 v[94:97], v[148:151], v[224:227], v[94:97]
	v_mfma_f32_16x16x32_bf16 v[90:93], v[156:159], v[224:227], v[90:93]
	v_mfma_f32_16x16x32_bf16 v[78:81], v[148:151], v[232:235], v[78:81]
	v_mfma_f32_16x16x32_bf16 v[74:77], v[156:159], v[232:235], v[74:77]
	v_mfma_f32_16x16x32_bf16 v[126:129], v[152:155], v[212:215], v[126:129]
	v_mfma_f32_16x16x32_bf16 v[122:125], v[174:177], v[212:215], v[122:125]
	v_mfma_f32_16x16x32_bf16 v[110:113], v[152:155], v[220:223], v[110:113]
	v_mfma_f32_16x16x32_bf16 v[106:109], v[174:177], v[220:223], v[106:109]
	v_mfma_f32_16x16x32_bf16 v[94:97], v[152:155], v[228:231], v[94:97]
	v_mfma_f32_16x16x32_bf16 v[90:93], v[174:177], v[228:231], v[90:93]
	v_mfma_f32_16x16x32_bf16 v[78:81], v[152:155], v[236:239], v[78:81]
	v_mfma_f32_16x16x32_bf16 v[74:77], v[174:177], v[236:239], v[74:77]
	v_mfma_f32_16x16x32_bf16 v[118:121], v[178:181], v[208:211], v[118:121]
	v_mfma_f32_16x16x32_bf16 v[114:117], v[200:203], v[208:211], v[114:117]
	v_mfma_f32_16x16x32_bf16 v[102:105], v[178:181], v[216:219], v[102:105]
	v_mfma_f32_16x16x32_bf16 v[98:101], v[200:203], v[216:219], v[98:101]
	v_mfma_f32_16x16x32_bf16 v[86:89], v[178:181], v[224:227], v[86:89]
	v_mfma_f32_16x16x32_bf16 v[82:85], v[200:203], v[224:227], v[82:85]
	v_mfma_f32_16x16x32_bf16 v[70:73], v[178:181], v[232:235], v[70:73]
	v_mfma_f32_16x16x32_bf16 v[66:69], v[200:203], v[232:235], v[66:69]
	v_mfma_f32_16x16x32_bf16 v[118:121], v[182:185], v[212:215], v[118:121]
	v_mfma_f32_16x16x32_bf16 v[114:117], v[204:207], v[212:215], v[114:117]
	v_mfma_f32_16x16x32_bf16 v[102:105], v[182:185], v[220:223], v[102:105]
	v_mfma_f32_16x16x32_bf16 v[98:101], v[204:207], v[220:223], v[98:101]
	v_mfma_f32_16x16x32_bf16 v[86:89], v[182:185], v[228:231], v[86:89]
	v_mfma_f32_16x16x32_bf16 v[82:85], v[204:207], v[228:231], v[82:85]
	v_mfma_f32_16x16x32_bf16 v[70:73], v[182:185], v[236:239], v[70:73]
	v_mfma_f32_16x16x32_bf16 v[66:69], v[204:207], v[236:239], v[66:69]
	s_barrier
	s_add_i32 s10, s40, s22
	v_lshl_add_u64 v[142:143], v[142:143], 0, s[94:95]
	s_mov_b32 m0, s10
	ds_read_b128 v[208:211], v146 offset:49152
	ds_read_b128 v[212:215], v146 offset:50176
	ds_read_b128 v[216:219], v146 offset:51200
	ds_read_b128 v[220:223], v146 offset:52224
	ds_read_b128 v[224:227], v146 offset:53248
	ds_read_b128 v[228:231], v146 offset:54272
	ds_read_b128 v[232:235], v146 offset:55296
	ds_read_b128 v[236:239], v146 offset:56320
	global_load_lds_dwordx4 v[142:143], off
	s_add_i32 m0, s10, 0x2000
	s_add_u32 s10, s14, 0x160080
	v_lshl_add_u64 v[142:143], v[160:161], 0, s[94:95]
	s_addc_u32 s11, s15, 0
	s_add_i32 s14, s41, s22
	global_load_lds_dwordx4 v[142:143], off
	v_lshl_add_u64 v[142:143], s[10:11], 0, v[134:135]
	s_mov_b32 m0, s14
	s_nop 0
	global_load_lds_dwordx4 v[142:143], off
	v_lshl_add_u64 v[142:143], s[10:11], 0, v[130:131]
	s_add_i32 m0, s14, 0x2000
	s_nop 0
	global_load_lds_dwordx4 v[142:143], off
	v_lshl_add_u64 v[142:143], v[240:241], 0, s[94:95]
	s_mov_b32 m0, s27
	s_nop 0
	global_load_lds_dwordx4 v[142:143], off
	v_lshl_add_u64 v[142:143], v[242:243], 0, s[94:95]
	s_mov_b32 m0, s28
	s_nop 0
	global_load_lds_dwordx4 v[142:143], off
	s_waitcnt vmcnt(8)
	s_waitcnt lgkmcnt(0)
	s_barrier
	s_waitcnt lgkmcnt(0)
	v_mfma_f32_16x16x32_bf16 v[60:63], v[148:151], v[208:211], v[60:63]
	v_mfma_f32_16x16x32_bf16 v[56:59], v[156:159], v[208:211], v[56:59]
	v_mfma_f32_16x16x32_bf16 v[44:47], v[148:151], v[216:219], v[44:47]
	v_mfma_f32_16x16x32_bf16 v[40:43], v[156:159], v[216:219], v[40:43]
	v_mfma_f32_16x16x32_bf16 v[28:31], v[148:151], v[224:227], v[28:31]
	v_mfma_f32_16x16x32_bf16 v[24:27], v[156:159], v[224:227], v[24:27]
	v_mfma_f32_16x16x32_bf16 v[20:23], v[148:151], v[232:235], v[20:23]
	v_mfma_f32_16x16x32_bf16 v[12:15], v[156:159], v[232:235], v[12:15]
	v_mfma_f32_16x16x32_bf16 v[60:63], v[152:155], v[212:215], v[60:63]
	v_mfma_f32_16x16x32_bf16 v[56:59], v[174:177], v[212:215], v[56:59]
	v_mfma_f32_16x16x32_bf16 v[44:47], v[152:155], v[220:223], v[44:47]
	v_mfma_f32_16x16x32_bf16 v[40:43], v[174:177], v[220:223], v[40:43]
	v_mfma_f32_16x16x32_bf16 v[28:31], v[152:155], v[228:231], v[28:31]
	v_mfma_f32_16x16x32_bf16 v[24:27], v[174:177], v[228:231], v[24:27]
	v_mfma_f32_16x16x32_bf16 v[20:23], v[152:155], v[236:239], v[20:23]
	v_mfma_f32_16x16x32_bf16 v[12:15], v[174:177], v[236:239], v[12:15]
	v_mfma_f32_16x16x32_bf16 v[52:55], v[178:181], v[208:211], v[52:55]
	v_mfma_f32_16x16x32_bf16 v[48:51], v[200:203], v[208:211], v[48:51]
	v_mfma_f32_16x16x32_bf16 v[36:39], v[178:181], v[216:219], v[36:39]
	v_mfma_f32_16x16x32_bf16 v[32:35], v[200:203], v[216:219], v[32:35]
	v_mfma_f32_16x16x32_bf16 v[16:19], v[178:181], v[224:227], v[16:19]
	v_mfma_f32_16x16x32_bf16 v[8:11], v[200:203], v[224:227], v[8:11]
	v_mfma_f32_16x16x32_bf16 v[4:7], v[178:181], v[232:235], v[4:7]
	v_mfma_f32_16x16x32_bf16 v[0:3], v[200:203], v[232:235], v[0:3]
	v_mfma_f32_16x16x32_bf16 v[52:55], v[182:185], v[212:215], v[52:55]
	v_mfma_f32_16x16x32_bf16 v[48:51], v[204:207], v[212:215], v[48:51]
	v_mfma_f32_16x16x32_bf16 v[36:39], v[182:185], v[220:223], v[36:39]
	v_mfma_f32_16x16x32_bf16 v[32:35], v[204:207], v[220:223], v[32:35]
	v_mfma_f32_16x16x32_bf16 v[16:19], v[182:185], v[228:231], v[16:19]
	v_mfma_f32_16x16x32_bf16 v[8:11], v[204:207], v[228:231], v[8:11]
	v_mfma_f32_16x16x32_bf16 v[4:7], v[182:185], v[236:239], v[4:7]
	v_mfma_f32_16x16x32_bf16 v[0:3], v[204:207], v[236:239], v[0:3]
	s_barrier
	s_add_i32 s36, s36, 2
	s_add_u32 s34, s34, 0x100
	s_addc_u32 s35, s35, 0
	s_cmpk_gt_u32 s36, 0x55
	s_mov_b64 s[10:11], s[12:13]
	s_cbranch_scc0 .LBB0_557
	s_setprio 0
	s_and_b64 vcc, exec, s[6:7]
	s_cbranch_vccz .LBB0_560
	s_barrier
